# DPP / permlane-swap lane exchanges instead of ds_bpermute round trips in the phase-3 q/kv RMS-norm reductions, the wkv item reduction and the phase-5 group-norm reduction (33 hops), on top of the prev
# baseline (speedup 1.0000x reference)
.LBB0_398:
	s_mul_hi_i32 s6, s70, 0x2aaaaaab
	s_lshr_b32 s0, s6, 31
	s_add_i32 s6, s6, s0
	s_mul_i32 s7, s6, 0xfffffd00
	s_add_i32 s0, s3, s7
	s_ashr_i32 s1, s0, 31
	s_lshl_b32 s34, s6, 8
	s_lshl_b64 s[0:1], s[0:1], 9
	v_readlane_b32 s40, v241, 8
	v_readlane_b32 s72, v240, 1
	v_readlane_b32 s41, v241, 9
	v_readlane_b32 s42, v241, 10
	v_readlane_b32 s43, v241, 11
	v_readlane_b32 s44, v241, 12
	v_readlane_b32 s45, v241, 13
	v_readlane_b32 s46, v241, 14
	v_readlane_b32 s47, v241, 15
	s_add_u32 s0, s40, s0
	v_readlane_b32 s76, v240, 5
	v_readlane_b32 s77, v240, 6
	v_mov_b32_e32 v12, v174
	s_addc_u32 s1, s41, s1
	s_mul_i32 s4, s6, 0x104000
	v_readlane_b32 s78, v240, 7
	v_readlane_b32 s79, v240, 8
	v_readlane_b32 s80, v240, 9
	v_readlane_b32 s81, v240, 10
	v_readlane_b32 s82, v240, 11
	v_readlane_b32 s83, v240, 12
	v_readlane_b32 s84, v240, 13
	v_readlane_b32 s85, v240, 14
	v_readlane_b32 s86, v240, 15
	v_readlane_b32 s87, v240, 16
	s_mov_b64 s[40:41], s[76:77]
	s_mul_hi_i32 s5, s34, 0x1040
	v_ashrrev_i32_e32 v118, 3, v12
	s_add_u32 s4, s40, s4
	v_and_b32_e32 v138, 7, v12
	v_add_u32_e32 v6, 64, v118
	s_addc_u32 s5, s41, s5
	v_lshlrev_b32_e32 v114, 4, v138
	v_ashrrev_i32_e32 v119, 31, v118
	v_ashrrev_i32_e32 v7, 31, v6
	v_lshl_add_u64 v[2:3], s[0:1], 0, v[114:115]
	v_lshlrev_b64 v[0:1], 9, v[118:119]
	v_lshlrev_b64 v[4:5], 9, v[6:7]
	v_lshl_add_u64 v[10:11], s[4:5], 0, v[114:115]
	v_lshl_add_u64 v[0:1], v[2:3], 0, v[0:1]
	v_lshl_add_u64 v[2:3], v[2:3], 0, v[4:5]
	v_mad_i64_i32 v[4:5], s[0:1], v118, s33, v[10:11]
	global_load_dwordx4 v[16:19], v[0:1], off
	global_load_dwordx4 v[20:23], v[2:3], off
	global_load_dwordx4 v[24:27], v[4:5], off
	v_mad_i64_i32 v[6:7], s[0:1], v6, s33, v[10:11]
	v_add_u32_e32 v8, 0x80, v118
	global_load_dwordx4 v[72:75], v[6:7], off
	v_mad_i64_i32 v[8:9], s[0:1], v8, s33, v[10:11]
	v_add_u32_e32 v14, 0xc0, v118
	global_load_dwordx4 v[64:67], v[8:9], off
	v_mad_i64_i32 v[10:11], s[0:1], v14, s33, v[10:11]
	global_load_dwordx4 v[60:63], v[10:11], off
	global_load_dwordx4 v[200:203], v[0:1], off offset:128
	global_load_dwordx4 v[204:207], v[2:3], off offset:128
	global_load_dwordx4 v[208:211], v[4:5], off offset:128
	global_load_dwordx4 v[212:215], v[6:7], off offset:128
	global_load_dwordx4 v[216:219], v[8:9], off offset:128
	global_load_dwordx4 v[220:223], v[10:11], off offset:128
	global_load_dwordx4 v[224:227], v[0:1], off offset:256
	global_load_dwordx4 v[228:231], v[2:3], off offset:256
	global_load_dwordx4 v[232:235], v[4:5], off offset:256
	global_load_dwordx4 v[236:239], v[6:7], off offset:256
	global_load_dwordx4 v[244:247], v[8:9], off offset:256
	global_load_dwordx4 v[248:251], v[10:11], off offset:256
	v_mul_lo_u32 v14, v118, s38
	v_add3_u32 v14, 0, v114, v14
	v_and_b32_e32 v13, 15, v12
	s_mov_b32 s0, 0xfffffc0
	v_and_b32_e32 v139, 48, v12
	v_and_b32_e32 v45, 0xcf, v12
	v_add_u32_e32 v44, 0, v139
	v_mul_u32_u24_e32 v175, 0x90, v45
	v_add_u32_e32 v15, 0x2400, v14
	v_add_u32_e32 v119, 0x4800, v14
	v_readlane_b32 s73, v240, 2
	v_readlane_b32 s74, v240, 3
	v_readlane_b32 s75, v240, 4
	s_mov_b64 s[42:43], s[78:79]
	s_mov_b64 s[44:45], s[80:81]
	s_mov_b64 s[46:47], s[82:83]
	s_mov_b64 s[48:49], s[84:85]
	s_mov_b64 s[50:51], s[86:87]
	s_waitcnt vmcnt(17)
	ds_write_b128 v14, v[16:19]
	s_waitcnt vmcnt(16)
	ds_write_b128 v14, v[20:23] offset:9216
	s_waitcnt vmcnt(15)
	v_and_b32_e32 v17, 0xffff0000, v24
	v_lshlrev_b32_e32 v16, 16, v24
	v_mul_f32_e32 v114, v17, v17
	v_fmac_f32_e32 v114, v16, v16
	v_lshlrev_b32_e32 v16, 16, v25
	v_fmac_f32_e32 v114, v16, v16
	v_and_b32_e32 v16, 0xffff0000, v25
	v_fmac_f32_e32 v114, v16, v16
	v_lshlrev_b32_e32 v16, 16, v26
	v_fmac_f32_e32 v114, v16, v16
	v_and_b32_e32 v16, 0xffff0000, v26
	v_fmac_f32_e32 v114, v16, v16
	v_lshlrev_b32_e32 v16, 16, v27
	ds_write_b128 v14, v[24:27] offset:18432
	s_waitcnt vmcnt(14)
	ds_write_b128 v14, v[72:75] offset:27648
	s_waitcnt vmcnt(13)
	ds_write_b128 v14, v[64:67] offset:36864
	s_waitcnt vmcnt(12)
	ds_write_b128 v14, v[60:63] offset:46080
	v_fmac_f32_e32 v114, v16, v16
	v_and_b32_e32 v16, 0xffff0000, v27
	v_fmac_f32_e32 v114, v16, v16
	s_waitcnt lgkmcnt(0)
	s_barrier
	v_lshrrev_b32_e32 v16, 2, v12
	v_and_or_b32 v13, v16, s0, v13
	v_mad_u64_u32 v[12:13], s[0:1], v13, s38, v[44:45]
	v_mad_u32_u24 v13, v45, s38, v44
	ds_read_b128 v[28:31], v12
	ds_read_b128 v[32:35], v12 offset:2304
	ds_read_b128 v[36:39], v12 offset:4608
	ds_read_b128 v[40:43], v12 offset:6912
	ds_read_b128 v[44:47], v13 offset:18432
	ds_read_b128 v[48:51], v13 offset:20736
	ds_read_b128 v[52:55], v13 offset:23040
	ds_read_b128 v[56:59], v13 offset:25344
	s_setprio 1
	s_waitcnt lgkmcnt(3)
	v_mfma_f32_16x16x32_bf16 v[80:83], v[28:31], v[44:47], 0
	s_waitcnt lgkmcnt(2)
	v_mfma_f32_16x16x32_bf16 v[84:87], v[28:31], v[48:51], 0
	s_waitcnt lgkmcnt(1)
	v_mfma_f32_16x16x32_bf16 v[92:95], v[28:31], v[52:55], 0
	s_waitcnt lgkmcnt(0)
	v_mfma_f32_16x16x32_bf16 v[28:31], v[28:31], v[56:59], 0
	v_mfma_f32_16x16x32_bf16 v[96:99], v[32:35], v[44:47], 0
	v_mfma_f32_16x16x32_bf16 v[100:103], v[32:35], v[48:51], 0
	v_mfma_f32_16x16x32_bf16 v[104:107], v[32:35], v[52:55], 0
	v_mfma_f32_16x16x32_bf16 v[32:35], v[32:35], v[56:59], 0
	v_mfma_f32_16x16x32_bf16 v[108:111], v[36:39], v[44:47], 0
	v_mfma_f32_16x16x32_bf16 v[140:143], v[36:39], v[48:51], 0
	v_mfma_f32_16x16x32_bf16 v[144:147], v[36:39], v[52:55], 0
	v_mfma_f32_16x16x32_bf16 v[36:39], v[36:39], v[56:59], 0
	v_mfma_f32_16x16x32_bf16 v[44:47], v[40:43], v[44:47], 0
	v_mfma_f32_16x16x32_bf16 v[48:51], v[40:43], v[48:51], 0
	v_mfma_f32_16x16x32_bf16 v[52:55], v[40:43], v[52:55], 0
	v_mfma_f32_16x16x32_bf16 v[40:43], v[40:43], v[56:59], 0
	s_setprio 0
	ds_read_b128 v[56:59], v12 offset:64
	ds_read_b128 v[148:151], v12 offset:2368
	ds_read_b128 v[152:155], v12 offset:4672
	ds_read_b128 v[156:159], v12 offset:6976
	ds_read_b128 v[160:163], v13 offset:18496
	ds_read_b128 v[166:169], v13 offset:20800
	ds_read_b128 v[170:173], v13 offset:23104
	ds_read_b128 v[176:179], v13 offset:25408
	s_setprio 1
	s_waitcnt lgkmcnt(3)
	v_mfma_f32_16x16x32_bf16 v[180:183], v[56:59], v[160:163], v[80:83]
	s_waitcnt lgkmcnt(2)
	v_mfma_f32_16x16x32_bf16 v[84:87], v[56:59], v[166:169], v[84:87]
	s_waitcnt lgkmcnt(1)
	v_mfma_f32_16x16x32_bf16 v[92:95], v[56:59], v[170:173], v[92:95]
	s_waitcnt lgkmcnt(0)
	v_mfma_f32_16x16x32_bf16 v[28:31], v[56:59], v[176:179], v[28:31]
	v_mfma_f32_16x16x32_bf16 v[56:59], v[148:151], v[160:163], v[96:99]
	v_mfma_f32_16x16x32_bf16 v[100:103], v[148:151], v[166:169], v[100:103]
	v_mfma_f32_16x16x32_bf16 v[32:35], v[148:151], v[176:179], v[32:35]
	v_mfma_f32_16x16x32_bf16 v[108:111], v[152:155], v[160:163], v[108:111]
	v_mfma_f32_16x16x32_bf16 v[140:143], v[152:155], v[166:169], v[140:143]
	v_mfma_f32_16x16x32_bf16 v[36:39], v[152:155], v[176:179], v[36:39]
	v_mfma_f32_16x16x32_bf16 v[44:47], v[156:159], v[160:163], v[44:47]
	v_mfma_f32_16x16x32_bf16 v[48:51], v[156:159], v[166:169], v[48:51]
	v_mfma_f32_16x16x32_bf16 v[52:55], v[156:159], v[170:173], v[52:55]
	v_mfma_f32_16x16x32_bf16 v[40:43], v[156:159], v[176:179], v[40:43]
	v_mfma_f32_16x16x32_bf16 v[184:187], v[148:151], v[170:173], v[104:107]
	v_mfma_f32_16x16x32_bf16 v[144:147], v[152:155], v[170:173], v[144:147]
	s_setprio 0
	v_add_u32_e32 v196, 0xd800, v14
	s_waitcnt vmcnt(11)
	v_mov_b32_e32 v16, v200
	v_mov_b32_e32 v17, v201
	v_mov_b32_e32 v18, v202
	v_mov_b32_e32 v19, v203
	ds_write_b128 v14, v[16:19] offset:55296
	s_waitcnt vmcnt(10)
	v_mov_b32_e32 v20, v204
	v_mov_b32_e32 v21, v205
	v_mov_b32_e32 v22, v206
	v_mov_b32_e32 v23, v207
	ds_write_b128 v14, v[20:23] offset:64512
	s_waitcnt vmcnt(9)
	v_mov_b32_e32 v24, v208
	v_mov_b32_e32 v25, v209
	v_mov_b32_e32 v26, v210
	v_mov_b32_e32 v27, v211
	ds_write_b128 v15, v[24:27] offset:64512
	s_waitcnt vmcnt(8)
	v_mov_b32_e32 v88, v212
	v_mov_b32_e32 v89, v213
	v_mov_b32_e32 v90, v214
	v_mov_b32_e32 v91, v215
	ds_write_b128 v119, v[88:91] offset:64512
	s_waitcnt vmcnt(7)
	v_mov_b32_e32 v76, v216
	v_mov_b32_e32 v77, v217
	v_mov_b32_e32 v78, v218
	v_mov_b32_e32 v79, v219
	ds_write_b128 v196, v[76:79] offset:36864
	s_waitcnt vmcnt(6)
	v_mov_b32_e32 v68, v220
	v_mov_b32_e32 v69, v221
	v_mov_b32_e32 v70, v222
	v_mov_b32_e32 v71, v223
	ds_write_b128 v196, v[68:71] offset:46080
	s_waitcnt lgkmcnt(0)
	s_barrier
	global_load_dwordx4 v[200:203], v[0:1], off offset:384
	global_load_dwordx4 v[204:207], v[2:3], off offset:384
	global_load_dwordx4 v[208:211], v[4:5], off offset:384
	global_load_dwordx4 v[212:215], v[6:7], off offset:384
	global_load_dwordx4 v[216:219], v[8:9], off offset:384
	global_load_dwordx4 v[220:223], v[10:11], off offset:384
	v_and_b32_e32 v192, 0xffff0000, v27
	v_lshlrev_b32_e32 v193, 16, v27
	v_and_b32_e32 v27, 0xffff0000, v24
	v_lshlrev_b32_e32 v24, 16, v24
	v_fmac_f32_e32 v114, v24, v24
	v_and_b32_e32 v194, 0xffff0000, v26
	v_lshlrev_b32_e32 v195, 16, v26
	v_and_b32_e32 v26, 0xffff0000, v25
	v_lshlrev_b32_e32 v25, 16, v25
	v_fmac_f32_e32 v114, v27, v27
	v_fmac_f32_e32 v114, v25, v25
	v_add3_u32 v139, s39, v139, v175
	v_fmac_f32_e32 v114, v26, v26
	ds_read_b128 v[24:27], v12 offset:55296
	ds_read_b128 v[152:155], v12 offset:57600
	ds_read_b128 v[156:159], v12 offset:59904
	ds_read_b128 v[160:163], v12 offset:62208
	ds_read_b128 v[166:169], v139
	ds_read_b128 v[170:173], v139 offset:2304
	ds_read_b128 v[176:179], v139 offset:4608
	ds_read_b128 v[188:191], v139 offset:6912
	v_fmac_f32_e32 v114, v195, v195
	v_fmac_f32_e32 v114, v194, v194
	v_fmac_f32_e32 v114, v193, v193
	v_fmac_f32_e32 v114, v192, v192
	s_setprio 1
	s_waitcnt lgkmcnt(3)
	v_mfma_f32_16x16x32_bf16 v[180:183], v[24:27], v[166:169], v[180:183]
	s_waitcnt lgkmcnt(2)
	v_mfma_f32_16x16x32_bf16 v[84:87], v[24:27], v[170:173], v[84:87]
	s_waitcnt lgkmcnt(1)
	v_mfma_f32_16x16x32_bf16 v[92:95], v[24:27], v[176:179], v[92:95]
	s_waitcnt lgkmcnt(0)
	v_mfma_f32_16x16x32_bf16 v[24:27], v[24:27], v[188:191], v[28:31]
	v_mfma_f32_16x16x32_bf16 v[28:31], v[152:155], v[166:169], v[56:59]
	v_mfma_f32_16x16x32_bf16 v[56:59], v[152:155], v[170:173], v[100:103]
	v_mfma_f32_16x16x32_bf16 v[100:103], v[152:155], v[176:179], v[184:187]
	v_mfma_f32_16x16x32_bf16 v[32:35], v[152:155], v[188:191], v[32:35]
	v_mfma_f32_16x16x32_bf16 v[108:111], v[156:159], v[166:169], v[108:111]
	v_mfma_f32_16x16x32_bf16 v[140:143], v[156:159], v[170:173], v[140:143]
	v_mfma_f32_16x16x32_bf16 v[36:39], v[156:159], v[188:191], v[36:39]
	v_mfma_f32_16x16x32_bf16 v[44:47], v[160:163], v[166:169], v[44:47]
	v_mfma_f32_16x16x32_bf16 v[48:51], v[160:163], v[170:173], v[48:51]
	v_mfma_f32_16x16x32_bf16 v[52:55], v[160:163], v[176:179], v[52:55]
	v_mfma_f32_16x16x32_bf16 v[40:43], v[160:163], v[188:191], v[40:43]
	v_mfma_f32_16x16x32_bf16 v[144:147], v[156:159], v[176:179], v[144:147]
	s_setprio 0
	ds_read_b128 v[152:155], v12 offset:55360
	ds_read_b128 v[156:159], v12 offset:57664
	ds_read_b128 v[160:163], v12 offset:59968
	ds_read_b128 v[166:169], v12 offset:62272
	ds_read_b128 v[170:173], v139 offset:64
	ds_read_b128 v[176:179], v139 offset:2368
	ds_read_b128 v[184:187], v139 offset:4672
	ds_read_b128 v[188:191], v139 offset:6976
	s_setprio 1
	s_waitcnt lgkmcnt(2)
	v_mfma_f32_16x16x32_bf16 v[84:87], v[152:155], v[176:179], v[84:87]
	s_waitcnt lgkmcnt(0)
	v_mfma_f32_16x16x32_bf16 v[24:27], v[152:155], v[188:191], v[24:27]
	v_mfma_f32_16x16x32_bf16 v[28:31], v[156:159], v[170:173], v[28:31]
	v_mfma_f32_16x16x32_bf16 v[56:59], v[156:159], v[176:179], v[56:59]
	v_mfma_f32_16x16x32_bf16 v[32:35], v[156:159], v[188:191], v[32:35]
	v_mfma_f32_16x16x32_bf16 v[140:143], v[160:163], v[176:179], v[140:143]
	v_mfma_f32_16x16x32_bf16 v[36:39], v[160:163], v[188:191], v[36:39]
	v_mfma_f32_16x16x32_bf16 v[44:47], v[166:169], v[170:173], v[44:47]
	v_mfma_f32_16x16x32_bf16 v[48:51], v[166:169], v[176:179], v[48:51]
	v_mfma_f32_16x16x32_bf16 v[52:55], v[166:169], v[184:187], v[52:55]
	v_mfma_f32_16x16x32_bf16 v[40:43], v[166:169], v[188:191], v[40:43]
	v_mfma_f32_16x16x32_bf16 v[180:183], v[152:155], v[170:173], v[180:183]
	v_mfma_f32_16x16x32_bf16 v[192:195], v[152:155], v[184:187], v[92:95]
	v_mfma_f32_16x16x32_bf16 v[152:155], v[156:159], v[184:187], v[100:103]
	v_mfma_f32_16x16x32_bf16 v[156:159], v[160:163], v[170:173], v[108:111]
	v_mfma_f32_16x16x32_bf16 v[144:147], v[160:163], v[184:187], v[144:147]
	s_setprio 0
	s_waitcnt vmcnt(11)
	v_mov_b32_e32 v16, v224
	v_mov_b32_e32 v17, v225
	v_mov_b32_e32 v18, v226
	v_mov_b32_e32 v19, v227
	ds_write_b128 v14, v[16:19]
	s_waitcnt vmcnt(10)
	v_mov_b32_e32 v20, v228
	v_mov_b32_e32 v21, v229
	v_mov_b32_e32 v22, v230
	v_mov_b32_e32 v23, v231
	ds_write_b128 v14, v[20:23] offset:9216
	s_waitcnt vmcnt(9)
	v_mov_b32_e32 v148, v232
	v_mov_b32_e32 v149, v233
	v_mov_b32_e32 v150, v234
	v_mov_b32_e32 v151, v235
	ds_write_b128 v14, v[148:151] offset:18432
	s_waitcnt vmcnt(8)
	v_mov_b32_e32 v104, v236
	v_mov_b32_e32 v105, v237
	v_mov_b32_e32 v106, v238
	v_mov_b32_e32 v107, v239
	ds_write_b128 v14, v[104:107] offset:27648
	s_waitcnt vmcnt(7)
	v_mov_b32_e32 v96, v244
	v_mov_b32_e32 v97, v245
	v_mov_b32_e32 v98, v246
	v_mov_b32_e32 v99, v247
	ds_write_b128 v14, v[96:99] offset:36864
	s_waitcnt vmcnt(6)
	v_mov_b32_e32 v80, v248
	v_mov_b32_e32 v81, v249
	v_mov_b32_e32 v82, v250
	v_mov_b32_e32 v83, v251
	ds_write_b128 v14, v[80:83] offset:46080
	s_waitcnt lgkmcnt(0)
	s_barrier
	s_nop 0
	s_nop 0
	v_lshlrev_b32_e32 v7, 16, v148
	v_and_b32_e32 v6, 0xffff0000, v148
	v_fmac_f32_e32 v114, v7, v7
	v_lshlrev_b32_e32 v5, 16, v149
	v_fmac_f32_e32 v114, v6, v6
	v_and_b32_e32 v4, 0xffff0000, v149
	v_fmac_f32_e32 v114, v5, v5
	v_and_b32_e32 v175, 0xffff0000, v151
	v_lshlrev_b32_e32 v188, 16, v151
	v_and_b32_e32 v189, 0xffff0000, v150
	v_lshlrev_b32_e32 v190, 16, v150
	v_fmac_f32_e32 v114, v4, v4
	ds_read_b128 v[4:7], v12
	ds_read_b128 v[8:11], v12 offset:2304
	ds_read_b128 v[148:151], v12 offset:4608
	ds_read_b128 v[160:163], v12 offset:6912
	ds_read_b128 v[166:169], v13 offset:18432
	ds_read_b128 v[170:173], v13 offset:20736
	ds_read_b128 v[176:179], v13 offset:23040
	ds_read_b128 v[184:187], v13 offset:25344
	v_fmac_f32_e32 v114, v190, v190
	v_fmac_f32_e32 v114, v189, v189
	v_fmac_f32_e32 v114, v188, v188
	v_fmac_f32_e32 v114, v175, v175
	s_setprio 1
	s_waitcnt lgkmcnt(3)
	v_mfma_f32_16x16x32_bf16 v[180:183], v[4:7], v[166:169], v[180:183]
	s_waitcnt lgkmcnt(2)
	v_mfma_f32_16x16x32_bf16 v[84:87], v[4:7], v[170:173], v[84:87]
	s_waitcnt lgkmcnt(1)
	v_mfma_f32_16x16x32_bf16 v[188:191], v[4:7], v[176:179], v[192:195]
	s_waitcnt lgkmcnt(0)
	v_mfma_f32_16x16x32_bf16 v[4:7], v[4:7], v[184:187], v[24:27]
	v_mfma_f32_16x16x32_bf16 v[24:27], v[8:11], v[166:169], v[28:31]
	v_mfma_f32_16x16x32_bf16 v[28:31], v[8:11], v[170:173], v[56:59]
	v_mfma_f32_16x16x32_bf16 v[56:59], v[8:11], v[176:179], v[152:155]
	v_mfma_f32_16x16x32_bf16 v[8:11], v[8:11], v[184:187], v[32:35]
	v_mfma_f32_16x16x32_bf16 v[32:35], v[148:151], v[166:169], v[156:159]
	v_mfma_f32_16x16x32_bf16 v[140:143], v[148:151], v[170:173], v[140:143]
	v_mfma_f32_16x16x32_bf16 v[36:39], v[148:151], v[184:187], v[36:39]
	v_mfma_f32_16x16x32_bf16 v[44:47], v[160:163], v[166:169], v[44:47]
	v_mfma_f32_16x16x32_bf16 v[48:51], v[160:163], v[170:173], v[48:51]
	v_mfma_f32_16x16x32_bf16 v[52:55], v[160:163], v[176:179], v[52:55]
	v_mfma_f32_16x16x32_bf16 v[40:43], v[160:163], v[184:187], v[40:43]
	v_mfma_f32_16x16x32_bf16 v[144:147], v[148:151], v[176:179], v[144:147]
	s_setprio 0
	ds_read_b128 v[148:151], v12 offset:64
	ds_read_b128 v[152:155], v12 offset:2368
	ds_read_b128 v[156:159], v12 offset:4672
	ds_read_b128 v[160:163], v12 offset:6976
	ds_read_b128 v[166:169], v13 offset:18496
	ds_read_b128 v[170:173], v13 offset:20800
	ds_read_b128 v[176:179], v13 offset:23104
	ds_read_b128 v[184:187], v13 offset:25408
	s_setprio 1
	s_waitcnt lgkmcnt(2)
	v_mfma_f32_16x16x32_bf16 v[84:87], v[148:151], v[170:173], v[84:87]
	s_waitcnt lgkmcnt(0)
	v_mfma_f32_16x16x32_bf16 v[4:7], v[148:151], v[184:187], v[4:7]
	v_mfma_f32_16x16x32_bf16 v[24:27], v[152:155], v[166:169], v[24:27]
	v_mfma_f32_16x16x32_bf16 v[28:31], v[152:155], v[170:173], v[28:31]
	v_mfma_f32_16x16x32_bf16 v[56:59], v[152:155], v[176:179], v[56:59]
	v_mfma_f32_16x16x32_bf16 v[8:11], v[152:155], v[184:187], v[8:11]
	v_mfma_f32_16x16x32_bf16 v[32:35], v[156:159], v[166:169], v[32:35]
	v_mfma_f32_16x16x32_bf16 v[140:143], v[156:159], v[170:173], v[140:143]
	v_mfma_f32_16x16x32_bf16 v[36:39], v[156:159], v[184:187], v[36:39]
	v_mfma_f32_16x16x32_bf16 v[44:47], v[160:163], v[166:169], v[44:47]
	v_mfma_f32_16x16x32_bf16 v[48:51], v[160:163], v[170:173], v[48:51]
	v_mfma_f32_16x16x32_bf16 v[52:55], v[160:163], v[176:179], v[52:55]
	v_mfma_f32_16x16x32_bf16 v[40:43], v[160:163], v[184:187], v[40:43]
	v_mfma_f32_16x16x32_bf16 v[180:183], v[148:151], v[166:169], v[180:183]
	v_mfma_f32_16x16x32_bf16 v[188:191], v[148:151], v[176:179], v[188:191]
	v_mfma_f32_16x16x32_bf16 v[144:147], v[156:159], v[176:179], v[144:147]
	s_setprio 0
	s_waitcnt vmcnt(5)
	v_mov_b32_e32 v16, v200
	v_mov_b32_e32 v17, v201
	v_mov_b32_e32 v18, v202
	v_mov_b32_e32 v19, v203
	ds_write_b128 v14, v[16:19] offset:55296
	s_waitcnt vmcnt(4)
	v_mov_b32_e32 v0, v204
	v_mov_b32_e32 v1, v205
	v_mov_b32_e32 v2, v206
	v_mov_b32_e32 v3, v207
	ds_write_b128 v14, v[0:3] offset:64512
	s_waitcnt vmcnt(3)
	v_mov_b32_e32 v20, v208
	v_mov_b32_e32 v21, v209
	v_mov_b32_e32 v22, v210
	v_mov_b32_e32 v23, v211
	ds_write_b128 v15, v[20:23] offset:64512
	s_waitcnt vmcnt(2)
	v_mov_b32_e32 v108, v212
	v_mov_b32_e32 v109, v213
	v_mov_b32_e32 v110, v214
	v_mov_b32_e32 v111, v215
	ds_write_b128 v119, v[108:111] offset:64512
	s_waitcnt vmcnt(1)
	v_mov_b32_e32 v100, v216
	v_mov_b32_e32 v101, v217
	v_mov_b32_e32 v102, v218
	v_mov_b32_e32 v103, v219
	ds_write_b128 v196, v[100:103] offset:36864
	s_waitcnt vmcnt(0)
	v_mov_b32_e32 v92, v220
	v_mov_b32_e32 v93, v221
	v_mov_b32_e32 v94, v222
	v_mov_b32_e32 v95, v223
	ds_write_b128 v196, v[92:95] offset:46080
	v_lshlrev_b32_e32 v3, 16, v20
	v_and_b32_e32 v2, 0xffff0000, v20
	v_fmac_f32_e32 v114, v3, v3
	v_lshlrev_b32_e32 v1, 16, v21
	v_fmac_f32_e32 v114, v2, v2
	v_and_b32_e32 v0, 0xffff0000, v21
	v_fmac_f32_e32 v114, v1, v1
	s_waitcnt lgkmcnt(0)
	s_barrier
	v_fmac_f32_e32 v114, v0, v0
	ds_read_b128 v[0:3], v12 offset:55296
	ds_read_b128 v[14:17], v12 offset:57600
	ds_read_b128 v[18:21], v12 offset:59904
	ds_read_b128 v[148:151], v12 offset:62208
	ds_read_b128 v[152:155], v139
	ds_read_b128 v[156:159], v139 offset:2304
	ds_read_b128 v[160:163], v139 offset:4608
	ds_read_b128 v[166:169], v139 offset:6912
	v_and_b32_e32 v119, 0xffff0000, v22
	v_lshlrev_b32_e32 v22, 16, v22
	v_fmac_f32_e32 v114, v22, v22
	v_and_b32_e32 v13, 0xffff0000, v23
	v_lshlrev_b32_e32 v23, 16, v23
	v_fmac_f32_e32 v114, v119, v119
	v_fmac_f32_e32 v114, v23, v23
	v_fmac_f32_e32 v114, v13, v13
	s_setprio 1
	s_waitcnt lgkmcnt(3)
	v_mfma_f32_16x16x32_bf16 v[170:173], v[0:3], v[152:155], v[180:183]
	s_waitcnt lgkmcnt(2)
	v_mfma_f32_16x16x32_bf16 v[176:179], v[0:3], v[156:159], v[84:87]
	s_waitcnt lgkmcnt(1)
	v_mfma_f32_16x16x32_bf16 v[180:183], v[0:3], v[160:163], v[188:191]
	s_waitcnt lgkmcnt(0)
	v_mfma_f32_16x16x32_bf16 v[0:3], v[0:3], v[166:169], v[4:7]
	v_mfma_f32_16x16x32_bf16 v[4:7], v[14:17], v[152:155], v[24:27]
	v_mfma_f32_16x16x32_bf16 v[22:25], v[14:17], v[156:159], v[28:31]
	v_mfma_f32_16x16x32_bf16 v[184:187], v[14:17], v[160:163], v[56:59]
	v_mfma_f32_16x16x32_bf16 v[8:11], v[14:17], v[166:169], v[8:11]
	v_mfma_f32_16x16x32_bf16 v[32:35], v[18:21], v[152:155], v[32:35]
	v_mfma_f32_16x16x32_bf16 v[140:143], v[18:21], v[156:159], v[140:143]
	v_mfma_f32_16x16x32_bf16 v[144:147], v[18:21], v[160:163], v[144:147]
	v_mfma_f32_16x16x32_bf16 v[16:19], v[18:21], v[166:169], v[36:39]
	v_mfma_f32_16x16x32_bf16 v[152:155], v[148:151], v[152:155], v[44:47]
	v_mfma_f32_16x16x32_bf16 v[156:159], v[148:151], v[156:159], v[48:51]
	v_mfma_f32_16x16x32_bf16 v[160:163], v[148:151], v[160:163], v[52:55]
	v_mfma_f32_16x16x32_bf16 v[148:151], v[148:151], v[166:169], v[40:43]
	s_setprio 0
	ds_read_b128 v[36:39], v12 offset:55360
	ds_read_b128 v[48:51], v12 offset:57664
	ds_read_b128 v[166:169], v12 offset:59968
	ds_read_b128 v[188:191], v12 offset:62272
	ds_read_b128 v[192:195], v139 offset:64
	ds_read_b128 v[196:199], v139 offset:2368
	ds_read_b128 v[200:203], v139 offset:4672
	ds_read_b128 v[204:207], v139 offset:6976
	s_setprio 1
	s_waitcnt lgkmcnt(3)
	v_mfma_f32_16x16x32_bf16 v[84:87], v[36:39], v[192:195], v[170:173]
	s_waitcnt lgkmcnt(2)
	v_mfma_f32_16x16x32_bf16 v[44:47], v[36:39], v[196:199], v[176:179]
	s_waitcnt lgkmcnt(1)
	v_mfma_f32_16x16x32_bf16 v[28:31], v[36:39], v[200:203], v[180:183]
	s_waitcnt lgkmcnt(0)
	v_mfma_f32_16x16x32_bf16 v[12:15], v[36:39], v[204:207], v[0:3]
	v_mfma_f32_16x16x32_bf16 v[56:59], v[48:51], v[192:195], v[4:7]
	v_mfma_f32_16x16x32_bf16 v[40:43], v[48:51], v[196:199], v[22:25]
	v_mfma_f32_16x16x32_bf16 v[24:27], v[48:51], v[200:203], v[184:187]
	v_mfma_f32_16x16x32_bf16 v[8:11], v[48:51], v[204:207], v[8:11]
	v_mfma_f32_16x16x32_bf16 v[52:55], v[166:169], v[192:195], v[32:35]
	v_mfma_f32_16x16x32_bf16 v[36:39], v[166:169], v[196:199], v[140:143]
	v_mfma_f32_16x16x32_bf16 v[20:23], v[166:169], v[200:203], v[144:147]
	v_mfma_f32_16x16x32_bf16 v[4:7], v[166:169], v[204:207], v[16:19]
	v_mfma_f32_16x16x32_bf16 v[48:51], v[188:191], v[192:195], v[152:155]
	v_mfma_f32_16x16x32_bf16 v[32:35], v[188:191], v[196:199], v[156:159]
	v_mfma_f32_16x16x32_bf16 v[16:19], v[188:191], v[200:203], v[160:163]
	v_mfma_f32_16x16x32_bf16 v[0:3], v[188:191], v[204:207], v[148:151]
	s_setprio 0
	v_cmp_lt_i32_e32 vcc, v129, v130
	s_waitcnt lgkmcnt(0)
	s_barrier
	v_lshl_add_u32 v118, v118, 2, s2
	v_cndmask_b32_e32 v119, v128, v129, vcc
	v_cmp_lt_i32_e32 vcc, v131, v130
	v_lshlrev_b32_e32 v119, 2, v119
	s_nop 0
	v_cndmask_b32_e32 v139, v128, v131, vcc
	v_cmp_lt_i32_e32 vcc, v132, v130
	v_lshlrev_b32_e32 v139, 2, v139
	s_nop 0
	v_cndmask_b32_e32 v140, v128, v132, vcc
	v_cmp_eq_u32_e32 vcc, 0, v138
	s_nop 1
	v_mov_b32_dpp v138, v114 quad_perm:[1,0,3,2] row_mask:0xf bank_mask:0xf
	v_lshlrev_b32_e32 v140, 2, v140
	s_waitcnt lgkmcnt(0)
	v_add_f32_e32 v114, v114, v138
	s_nop 1
	v_mov_b32_dpp v138, v114 quad_perm:[2,3,0,1] row_mask:0xf bank_mask:0xf
	s_waitcnt lgkmcnt(0)
	v_add_f32_e32 v114, v114, v138
	s_nop 1
	v_mov_b32_dpp v138, v114 row_shl:4 row_mask:0xf bank_mask:0x5
	s_nop 1
	v_mov_b32_dpp v138, v114 row_shr:4 row_mask:0xf bank_mask:0xa
	s_and_saveexec_b64 s[4:5], vcc
	s_cbranch_execz .LBB0_400
	s_waitcnt lgkmcnt(0)
	v_add_f32_e32 v114, v114, v138
	v_fmamk_f32 v114, v114, 0x3b800000, v133
	v_mul_f32_e32 v138, 0x4b800000, v114
	v_cmp_gt_f32_e64 s[0:1], s68, v114
	s_nop 1
	v_cndmask_b32_e64 v114, v114, v138, s[0:1]
	v_rsq_f32_e32 v114, v114
	s_nop 0
	v_mul_f32_e32 v138, 0x45800000, v114
	v_cndmask_b32_e64 v114, v114, v138, s[0:1]
	ds_write_b32 v118, v114
.LBB0_400:
	s_or_b64 exec, exec, s[4:5]
	v_lshlrev_b32_e32 v114, 16, v72
	v_and_b32_e32 v72, 0xffff0000, v72
	v_mul_f32_e32 v72, v72, v72
	v_fmac_f32_e32 v72, v114, v114
	v_lshlrev_b32_e32 v114, 16, v73
	v_fmac_f32_e32 v72, v114, v114
	v_and_b32_e32 v73, 0xffff0000, v73
	v_fmac_f32_e32 v72, v73, v73
	v_lshlrev_b32_e32 v73, 16, v74
	v_fmac_f32_e32 v72, v73, v73
	v_and_b32_e32 v73, 0xffff0000, v74
	v_fmac_f32_e32 v72, v73, v73
	v_lshlrev_b32_e32 v73, 16, v75
	v_fmac_f32_e32 v72, v73, v73
	v_and_b32_e32 v73, 0xffff0000, v75
	v_fmac_f32_e32 v72, v73, v73
	v_and_b32_e32 v114, 0xffff0000, v88
	v_lshlrev_b32_e32 v88, 16, v88
	v_fmac_f32_e32 v72, v88, v88
	v_and_b32_e32 v73, 0xffff0000, v91
	v_lshlrev_b32_e32 v74, 16, v91
	v_and_b32_e32 v91, 0xffff0000, v89
	v_lshlrev_b32_e32 v89, 16, v89
	v_fmac_f32_e32 v72, v114, v114
	v_fmac_f32_e32 v72, v89, v89
	v_and_b32_e32 v75, 0xffff0000, v90
	v_lshlrev_b32_e32 v90, 16, v90
	v_fmac_f32_e32 v72, v91, v91
	v_fmac_f32_e32 v72, v90, v90
	v_fmac_f32_e32 v72, v75, v75
	v_fmac_f32_e32 v72, v74, v74
	v_fmac_f32_e32 v72, v73, v73
	v_and_b32_e32 v91, 0xffff0000, v104
	v_lshlrev_b32_e32 v104, 16, v104
	v_fmac_f32_e32 v72, v104, v104
	v_lshlrev_b32_e32 v90, 16, v105
	v_fmac_f32_e32 v72, v91, v91
	v_and_b32_e32 v89, 0xffff0000, v105
	v_fmac_f32_e32 v72, v90, v90
	v_lshlrev_b32_e32 v88, 16, v106
	v_fmac_f32_e32 v72, v89, v89
	v_and_b32_e32 v75, 0xffff0000, v106
	v_fmac_f32_e32 v72, v88, v88
	v_lshlrev_b32_e32 v74, 16, v107
	v_fmac_f32_e32 v72, v75, v75
	v_and_b32_e32 v73, 0xffff0000, v107
	v_fmac_f32_e32 v72, v74, v74
	v_fmac_f32_e32 v72, v73, v73
	v_lshlrev_b32_e32 v104, 16, v108
	v_and_b32_e32 v91, 0xffff0000, v108
	v_fmac_f32_e32 v72, v104, v104
	v_lshlrev_b32_e32 v90, 16, v109
	v_fmac_f32_e32 v72, v91, v91
	v_and_b32_e32 v89, 0xffff0000, v109
	v_fmac_f32_e32 v72, v90, v90
	v_lshlrev_b32_e32 v88, 16, v110
	v_fmac_f32_e32 v72, v89, v89
	v_and_b32_e32 v75, 0xffff0000, v110
	v_fmac_f32_e32 v72, v88, v88
	v_lshlrev_b32_e32 v74, 16, v111
	v_fmac_f32_e32 v72, v75, v75
	v_and_b32_e32 v73, 0xffff0000, v111
	v_fmac_f32_e32 v72, v74, v74
	v_fmac_f32_e32 v72, v73, v73
	s_nop 1
	v_mov_b32_dpp v73, v72 quad_perm:[1,0,3,2] row_mask:0xf bank_mask:0xf
	s_waitcnt lgkmcnt(0)
	v_add_f32_e32 v72, v72, v73
	s_nop 1
	v_mov_b32_dpp v73, v72 quad_perm:[2,3,0,1] row_mask:0xf bank_mask:0xf
	s_waitcnt lgkmcnt(0)
	v_add_f32_e32 v72, v72, v73
	s_nop 1
	v_mov_b32_dpp v73, v72 row_shl:4 row_mask:0xf bank_mask:0x5
	s_nop 1
	v_mov_b32_dpp v73, v72 row_shr:4 row_mask:0xf bank_mask:0xa
	s_and_saveexec_b64 s[4:5], vcc
	s_cbranch_execz .LBB0_402
	s_waitcnt lgkmcnt(0)
	v_add_f32_e32 v72, v72, v73
	v_fmamk_f32 v72, v72, 0x3b800000, v133
	v_mul_f32_e32 v73, 0x4b800000, v72
	v_cmp_gt_f32_e64 s[0:1], s68, v72
	s_nop 1
	v_cndmask_b32_e64 v72, v72, v73, s[0:1]
	v_rsq_f32_e32 v72, v72
	s_nop 0
	v_mul_f32_e32 v73, 0x45800000, v72
	v_cndmask_b32_e64 v72, v72, v73, s[0:1]
	ds_write_b32 v118, v72 offset:256
.LBB0_402:
	s_or_b64 exec, exec, s[4:5]
	v_lshlrev_b32_e32 v72, 16, v64
	v_and_b32_e32 v64, 0xffff0000, v64
	v_mul_f32_e32 v64, v64, v64
	v_fmac_f32_e32 v64, v72, v72
	v_lshlrev_b32_e32 v72, 16, v65
	v_fmac_f32_e32 v64, v72, v72
	v_and_b32_e32 v65, 0xffff0000, v65
	v_fmac_f32_e32 v64, v65, v65
	v_lshlrev_b32_e32 v65, 16, v66
	v_fmac_f32_e32 v64, v65, v65
	v_and_b32_e32 v65, 0xffff0000, v66
	v_fmac_f32_e32 v64, v65, v65
	v_lshlrev_b32_e32 v65, 16, v67
	v_fmac_f32_e32 v64, v65, v65
	v_and_b32_e32 v65, 0xffff0000, v67
	v_fmac_f32_e32 v64, v65, v65
	v_and_b32_e32 v75, 0xffff0000, v76
	v_lshlrev_b32_e32 v76, 16, v76
	v_fmac_f32_e32 v64, v76, v76
	v_lshlrev_b32_e32 v74, 16, v77
	v_fmac_f32_e32 v64, v75, v75
	s_waitcnt lgkmcnt(0)
	v_and_b32_e32 v73, 0xffff0000, v77
	v_fmac_f32_e32 v64, v74, v74
	v_lshlrev_b32_e32 v72, 16, v78
	v_fmac_f32_e32 v64, v73, v73
	v_and_b32_e32 v67, 0xffff0000, v78
	v_fmac_f32_e32 v64, v72, v72
	v_lshlrev_b32_e32 v66, 16, v79
	v_fmac_f32_e32 v64, v67, v67
	v_and_b32_e32 v65, 0xffff0000, v79
	v_fmac_f32_e32 v64, v66, v66
	v_fmac_f32_e32 v64, v65, v65
	v_lshlrev_b32_e32 v76, 16, v96
	v_and_b32_e32 v75, 0xffff0000, v96
	v_fmac_f32_e32 v64, v76, v76
	v_lshlrev_b32_e32 v74, 16, v97
	v_fmac_f32_e32 v64, v75, v75
	v_and_b32_e32 v73, 0xffff0000, v97
	v_fmac_f32_e32 v64, v74, v74
	v_lshlrev_b32_e32 v72, 16, v98
	v_fmac_f32_e32 v64, v73, v73
	v_and_b32_e32 v67, 0xffff0000, v98
	v_fmac_f32_e32 v64, v72, v72
	v_lshlrev_b32_e32 v66, 16, v99
	v_fmac_f32_e32 v64, v67, v67
	v_and_b32_e32 v65, 0xffff0000, v99
	v_fmac_f32_e32 v64, v66, v66
	v_fmac_f32_e32 v64, v65, v65
	v_lshlrev_b32_e32 v76, 16, v100
	v_and_b32_e32 v75, 0xffff0000, v100
	v_fmac_f32_e32 v64, v76, v76
	v_lshlrev_b32_e32 v74, 16, v101
	v_fmac_f32_e32 v64, v75, v75
	v_and_b32_e32 v73, 0xffff0000, v101
	v_fmac_f32_e32 v64, v74, v74
	v_lshlrev_b32_e32 v72, 16, v102
	v_fmac_f32_e32 v64, v73, v73
	v_and_b32_e32 v67, 0xffff0000, v102
	v_fmac_f32_e32 v64, v72, v72
	v_lshlrev_b32_e32 v66, 16, v103
	v_fmac_f32_e32 v64, v67, v67
	v_and_b32_e32 v65, 0xffff0000, v103
	v_fmac_f32_e32 v64, v66, v66
	v_fmac_f32_e32 v64, v65, v65
	s_nop 1
	v_mov_b32_dpp v65, v64 quad_perm:[1,0,3,2] row_mask:0xf bank_mask:0xf
	s_waitcnt lgkmcnt(0)
	v_add_f32_e32 v64, v64, v65
	s_nop 1
	v_mov_b32_dpp v65, v64 quad_perm:[2,3,0,1] row_mask:0xf bank_mask:0xf
	s_waitcnt lgkmcnt(0)
	v_add_f32_e32 v64, v64, v65
	s_nop 1
	v_mov_b32_dpp v65, v64 row_shl:4 row_mask:0xf bank_mask:0x5
	s_nop 1
	v_mov_b32_dpp v65, v64 row_shr:4 row_mask:0xf bank_mask:0xa
	s_and_saveexec_b64 s[4:5], vcc
	s_cbranch_execz .LBB0_404
	s_waitcnt lgkmcnt(0)
	v_add_f32_e32 v64, v64, v65
	v_fmamk_f32 v64, v64, 0x3b800000, v133
	v_mul_f32_e32 v65, 0x4b800000, v64
	v_cmp_gt_f32_e64 s[0:1], s68, v64
	s_nop 1
	v_cndmask_b32_e64 v64, v64, v65, s[0:1]
	v_rsq_f32_e32 v64, v64
	s_nop 0
	v_mul_f32_e32 v65, 0x45800000, v64
	v_cndmask_b32_e64 v64, v64, v65, s[0:1]
	ds_write_b32 v118, v64 offset:512
.LBB0_404:
	s_or_b64 exec, exec, s[4:5]
	v_lshlrev_b32_e32 v64, 16, v60
	v_and_b32_e32 v60, 0xffff0000, v60
	v_mul_f32_e32 v60, v60, v60
	v_fmac_f32_e32 v60, v64, v64
	v_lshlrev_b32_e32 v64, 16, v61
	v_fmac_f32_e32 v60, v64, v64
	v_and_b32_e32 v61, 0xffff0000, v61
	v_fmac_f32_e32 v60, v61, v61
	v_lshlrev_b32_e32 v61, 16, v62
	v_fmac_f32_e32 v60, v61, v61
	v_and_b32_e32 v61, 0xffff0000, v62
	v_fmac_f32_e32 v60, v61, v61
	v_lshlrev_b32_e32 v61, 16, v63
	v_fmac_f32_e32 v60, v61, v61
	v_and_b32_e32 v61, 0xffff0000, v63
	v_fmac_f32_e32 v60, v61, v61
	v_and_b32_e32 v67, 0xffff0000, v68
	v_lshlrev_b32_e32 v68, 16, v68
	v_fmac_f32_e32 v60, v68, v68
	v_lshlrev_b32_e32 v66, 16, v69
	v_fmac_f32_e32 v60, v67, v67
	s_waitcnt lgkmcnt(0)
	v_and_b32_e32 v65, 0xffff0000, v69
	v_fmac_f32_e32 v60, v66, v66
	v_lshlrev_b32_e32 v64, 16, v70
	v_fmac_f32_e32 v60, v65, v65
	v_and_b32_e32 v63, 0xffff0000, v70
	v_fmac_f32_e32 v60, v64, v64
	v_lshlrev_b32_e32 v62, 16, v71
	v_fmac_f32_e32 v60, v63, v63
	v_and_b32_e32 v61, 0xffff0000, v71
	v_fmac_f32_e32 v60, v62, v62
	v_fmac_f32_e32 v60, v61, v61
	v_lshlrev_b32_e32 v68, 16, v80
	v_and_b32_e32 v67, 0xffff0000, v80
	v_fmac_f32_e32 v60, v68, v68
	v_lshlrev_b32_e32 v66, 16, v81
	v_fmac_f32_e32 v60, v67, v67
	v_and_b32_e32 v65, 0xffff0000, v81
	v_fmac_f32_e32 v60, v66, v66
	v_lshlrev_b32_e32 v64, 16, v82
	v_fmac_f32_e32 v60, v65, v65
	v_and_b32_e32 v63, 0xffff0000, v82
	v_fmac_f32_e32 v60, v64, v64
	v_lshlrev_b32_e32 v62, 16, v83
	v_fmac_f32_e32 v60, v63, v63
	v_and_b32_e32 v61, 0xffff0000, v83
	v_fmac_f32_e32 v60, v62, v62
	v_fmac_f32_e32 v60, v61, v61
	v_lshlrev_b32_e32 v68, 16, v92
	v_and_b32_e32 v67, 0xffff0000, v92
	v_fmac_f32_e32 v60, v68, v68
	v_lshlrev_b32_e32 v66, 16, v93
	v_fmac_f32_e32 v60, v67, v67
	v_and_b32_e32 v65, 0xffff0000, v93
	v_fmac_f32_e32 v60, v66, v66
	v_lshlrev_b32_e32 v64, 16, v94
	v_fmac_f32_e32 v60, v65, v65
	v_and_b32_e32 v63, 0xffff0000, v94
	v_fmac_f32_e32 v60, v64, v64
	v_lshlrev_b32_e32 v62, 16, v95
	v_fmac_f32_e32 v60, v63, v63
	v_and_b32_e32 v61, 0xffff0000, v95
	v_fmac_f32_e32 v60, v62, v62
	v_fmac_f32_e32 v60, v61, v61
	s_nop 1
	v_mov_b32_dpp v61, v60 quad_perm:[1,0,3,2] row_mask:0xf bank_mask:0xf
	s_waitcnt lgkmcnt(0)
	v_add_f32_e32 v60, v60, v61
	s_nop 1
	v_mov_b32_dpp v61, v60 quad_perm:[2,3,0,1] row_mask:0xf bank_mask:0xf
	s_waitcnt lgkmcnt(0)
	v_add_f32_e32 v60, v60, v61
	s_nop 1
	v_mov_b32_dpp v61, v60 row_shl:4 row_mask:0xf bank_mask:0x5
	s_nop 1
	v_mov_b32_dpp v61, v60 row_shr:4 row_mask:0xf bank_mask:0xa
	s_and_saveexec_b64 s[0:1], vcc
	s_cbranch_execz .LBB0_406
	s_waitcnt lgkmcnt(0)
	v_add_f32_e32 v60, v60, v61
	v_fmamk_f32 v60, v60, 0x3b800000, v133
	v_mul_f32_e32 v61, 0x4b800000, v60
	v_cmp_gt_f32_e32 vcc, s68, v60
	s_nop 1
	v_cndmask_b32_e32 v60, v60, v61, vcc
	v_rsq_f32_e32 v60, v60
	s_nop 0
	v_mul_f32_e32 v61, 0x45800000, v60
	v_cndmask_b32_e32 v60, v60, v61, vcc
	ds_write_b32 v118, v60 offset:768

.LBB0_745:
	s_or_b64 exec, exec, s[0:1]
	s_nop 1
	v_lshlrev_b32_e32 v96, 16, v24
	v_and_b32_e32 v24, 0xffff0000, v24
	v_mul_f32_e32 v97, v24, v24
	v_fmac_f32_e32 v97, v96, v96
	v_lshlrev_b32_e32 v24, 16, v25
	v_fmac_f32_e32 v97, v24, v24
	v_and_b32_e32 v24, 0xffff0000, v25
	v_fmac_f32_e32 v97, v24, v24
	v_lshlrev_b32_e32 v24, 16, v26
	v_fmac_f32_e32 v97, v24, v24
	v_and_b32_e32 v24, 0xffff0000, v26
	v_fmac_f32_e32 v97, v24, v24
	v_lshlrev_b32_e32 v24, 16, v27
	v_fmac_f32_e32 v97, v24, v24
	v_and_b32_e32 v24, 0xffff0000, v27
	v_fmac_f32_e32 v97, v24, v24
	v_and_b32_e32 v24, 0xffff0000, v35
	v_lshlrev_b32_e32 v25, 16, v35
	v_and_b32_e32 v35, 0xffff0000, v32
	v_lshlrev_b32_e32 v32, 16, v32
	v_fmac_f32_e32 v97, v32, v32
	v_and_b32_e32 v26, 0xffff0000, v34
	v_lshlrev_b32_e32 v27, 16, v34
	v_and_b32_e32 v34, 0xffff0000, v33
	v_lshlrev_b32_e32 v33, 16, v33
	v_fmac_f32_e32 v97, v35, v35
	v_fmac_f32_e32 v97, v33, v33
	v_fmac_f32_e32 v97, v34, v34
	v_fmac_f32_e32 v97, v27, v27
	v_fmac_f32_e32 v97, v26, v26
	v_fmac_f32_e32 v97, v25, v25
	v_fmac_f32_e32 v97, v24, v24
	s_setprio 0
	v_and_b32_e32 v25, 64, v183
	v_xor_b32_e32 v24, 1, v183
	v_add_u32_e32 v26, 64, v25
	v_cmp_lt_i32_e64 s[0:1], v24, v26
	v_xor_b32_e32 v25, 2, v183
	v_xor_b32_e32 v33, 4, v183
	v_cndmask_b32_e64 v24, v183, v24, s[0:1]
	v_lshlrev_b32_e32 v24, 2, v24
	s_nop 1
	v_mov_b32_dpp v27, v97 quad_perm:[1,0,3,2] row_mask:0xf bank_mask:0xf
	v_cmp_lt_i32_e64 s[0:1], v25, v26
	s_waitcnt lgkmcnt(0)
	s_barrier
	s_waitcnt lgkmcnt(0)
	v_add_f32_e32 v27, v97, v27
	v_cndmask_b32_e64 v25, v183, v25, s[0:1]
	v_lshlrev_b32_e32 v25, 2, v25
	s_nop 1
	v_mov_b32_dpp v32, v27 quad_perm:[2,3,0,1] row_mask:0xf bank_mask:0xf
	v_cmp_lt_i32_e64 s[0:1], v33, v26
	s_waitcnt lgkmcnt(0)
	v_add_f32_e32 v32, v27, v32
	v_cndmask_b32_e64 v26, v183, v33, s[0:1]
	v_lshlrev_b32_e32 v26, 2, v26
	s_nop 1
	v_mov_b32_dpp v33, v32 row_shl:4 row_mask:0xf bank_mask:0x5
	s_nop 1
	v_mov_b32_dpp v33, v32 row_shr:4 row_mask:0xf bank_mask:0xa
	v_cmp_eq_u32_e64 s[0:1], 0, v186
	v_lshl_add_u32 v27, v162, 2, s3
	s_and_saveexec_b64 s[6:7], s[0:1]
	s_cbranch_execz .LBB0_747
	s_waitcnt lgkmcnt(0)
	v_add_f32_e32 v32, v32, v33
	v_fmamk_f32 v32, v32, 0x3c000000, v184
	v_mul_f32_e32 v33, 0x4b800000, v32
	v_cmp_gt_f32_e64 s[4:5], s13, v32
	s_nop 1
	v_cndmask_b32_e64 v32, v32, v33, s[4:5]
	v_rsq_f32_e32 v32, v32
	s_nop 0
	v_mul_f32_e32 v33, 0x45800000, v32
	v_cndmask_b32_e64 v32, v32, v33, s[4:5]
	ds_write_b32 v27, v32
.LBB0_747:
	s_or_b64 exec, exec, s[6:7]
	v_lshlrev_b32_e32 v32, 16, v12
	v_and_b32_e32 v12, 0xffff0000, v12
	v_mul_f32_e32 v12, v12, v12
	v_fmac_f32_e32 v12, v32, v32
	v_lshlrev_b32_e32 v32, 16, v13
	v_fmac_f32_e32 v12, v32, v32
	v_and_b32_e32 v13, 0xffff0000, v13
	v_fmac_f32_e32 v12, v13, v13
	v_lshlrev_b32_e32 v13, 16, v14
	v_fmac_f32_e32 v12, v13, v13
	v_and_b32_e32 v13, 0xffff0000, v14
	v_fmac_f32_e32 v12, v13, v13
	v_lshlrev_b32_e32 v13, 16, v15
	v_fmac_f32_e32 v12, v13, v13
	v_and_b32_e32 v13, 0xffff0000, v15
	v_fmac_f32_e32 v12, v13, v13
	v_and_b32_e32 v32, 0xffff0000, v20
	v_lshlrev_b32_e32 v20, 16, v20
	v_fmac_f32_e32 v12, v20, v20
	v_and_b32_e32 v13, 0xffff0000, v23
	v_lshlrev_b32_e32 v14, 16, v23
	v_and_b32_e32 v23, 0xffff0000, v21
	v_lshlrev_b32_e32 v21, 16, v21
	v_fmac_f32_e32 v12, v32, v32
	v_fmac_f32_e32 v12, v21, v21
	v_and_b32_e32 v15, 0xffff0000, v22
	v_lshlrev_b32_e32 v22, 16, v22
	v_fmac_f32_e32 v12, v23, v23
	v_fmac_f32_e32 v12, v22, v22
	v_fmac_f32_e32 v12, v15, v15
	v_fmac_f32_e32 v12, v14, v14
	v_fmac_f32_e32 v12, v13, v13
	s_nop 1
	v_mov_b32_dpp v13, v12 quad_perm:[1,0,3,2] row_mask:0xf bank_mask:0xf
	s_waitcnt lgkmcnt(0)
	v_add_f32_e32 v12, v12, v13
	s_nop 1
	v_mov_b32_dpp v13, v12 quad_perm:[2,3,0,1] row_mask:0xf bank_mask:0xf
	s_waitcnt lgkmcnt(0)
	v_add_f32_e32 v12, v12, v13
	s_nop 1
	v_mov_b32_dpp v13, v12 row_shl:4 row_mask:0xf bank_mask:0x5
	s_nop 1
	v_mov_b32_dpp v13, v12 row_shr:4 row_mask:0xf bank_mask:0xa
	s_and_saveexec_b64 s[6:7], s[0:1]
	s_cbranch_execz .LBB0_749
	s_waitcnt lgkmcnt(0)
	v_add_f32_e32 v12, v12, v13
	v_fmamk_f32 v12, v12, 0x3c000000, v184
	v_mul_f32_e32 v13, 0x4b800000, v12
	v_cmp_gt_f32_e64 s[4:5], s13, v12
	s_nop 1
	v_cndmask_b32_e64 v12, v12, v13, s[4:5]
	v_rsq_f32_e32 v12, v12
	s_nop 0
	v_mul_f32_e32 v13, 0x45800000, v12
	v_cndmask_b32_e64 v12, v12, v13, s[4:5]
	ds_write_b32 v27, v12 offset:256
.LBB0_749:
	s_or_b64 exec, exec, s[6:7]
	v_lshlrev_b32_e32 v12, 16, v4
	v_and_b32_e32 v4, 0xffff0000, v4
	v_mul_f32_e32 v4, v4, v4
	v_fmac_f32_e32 v4, v12, v12
	v_lshlrev_b32_e32 v12, 16, v5
	v_fmac_f32_e32 v4, v12, v12
	v_and_b32_e32 v5, 0xffff0000, v5
	v_fmac_f32_e32 v4, v5, v5
	v_lshlrev_b32_e32 v5, 16, v6
	v_fmac_f32_e32 v4, v5, v5
	v_and_b32_e32 v5, 0xffff0000, v6
	v_fmac_f32_e32 v4, v5, v5
	v_lshlrev_b32_e32 v5, 16, v7
	v_fmac_f32_e32 v4, v5, v5
	v_and_b32_e32 v5, 0xffff0000, v7
	v_fmac_f32_e32 v4, v5, v5
	v_and_b32_e32 v15, 0xffff0000, v16
	v_lshlrev_b32_e32 v16, 16, v16
	v_fmac_f32_e32 v4, v16, v16
	v_lshlrev_b32_e32 v14, 16, v17
	v_fmac_f32_e32 v4, v15, v15
	s_waitcnt lgkmcnt(0)
	v_and_b32_e32 v13, 0xffff0000, v17
	v_fmac_f32_e32 v4, v14, v14
	v_lshlrev_b32_e32 v12, 16, v18
	v_fmac_f32_e32 v4, v13, v13
	v_and_b32_e32 v7, 0xffff0000, v18
	v_fmac_f32_e32 v4, v12, v12
	v_lshlrev_b32_e32 v6, 16, v19
	v_fmac_f32_e32 v4, v7, v7
	v_and_b32_e32 v5, 0xffff0000, v19
	v_fmac_f32_e32 v4, v6, v6
	v_fmac_f32_e32 v4, v5, v5
	s_nop 1
	v_mov_b32_dpp v5, v4 quad_perm:[1,0,3,2] row_mask:0xf bank_mask:0xf
	s_waitcnt lgkmcnt(0)
	v_add_f32_e32 v4, v4, v5
	s_nop 1
	v_mov_b32_dpp v5, v4 quad_perm:[2,3,0,1] row_mask:0xf bank_mask:0xf
	s_waitcnt lgkmcnt(0)
	v_add_f32_e32 v4, v4, v5
	s_nop 1
	v_mov_b32_dpp v5, v4 row_shl:4 row_mask:0xf bank_mask:0x5
	s_nop 1
	v_mov_b32_dpp v5, v4 row_shr:4 row_mask:0xf bank_mask:0xa
	s_and_saveexec_b64 s[6:7], s[0:1]
	s_cbranch_execz .LBB0_751
	s_waitcnt lgkmcnt(0)
	v_add_f32_e32 v4, v4, v5
	v_fmamk_f32 v4, v4, 0x3c000000, v184
	v_mul_f32_e32 v5, 0x4b800000, v4
	v_cmp_gt_f32_e64 s[4:5], s13, v4
	s_nop 1
	v_cndmask_b32_e64 v4, v4, v5, s[4:5]
	v_rsq_f32_e32 v4, v4
	s_nop 0
	v_mul_f32_e32 v5, 0x45800000, v4
	v_cndmask_b32_e64 v4, v4, v5, s[4:5]
	ds_write_b32 v27, v4 offset:512
.LBB0_751:
	s_or_b64 exec, exec, s[6:7]
	v_lshlrev_b32_e32 v4, 16, v0
	v_and_b32_e32 v0, 0xffff0000, v0
	v_mul_f32_e32 v0, v0, v0
	v_fmac_f32_e32 v0, v4, v4
	v_lshlrev_b32_e32 v4, 16, v1
	v_fmac_f32_e32 v0, v4, v4
	v_and_b32_e32 v1, 0xffff0000, v1
	v_fmac_f32_e32 v0, v1, v1
	v_lshlrev_b32_e32 v1, 16, v2
	v_fmac_f32_e32 v0, v1, v1
	v_and_b32_e32 v1, 0xffff0000, v2
	v_fmac_f32_e32 v0, v1, v1
	v_lshlrev_b32_e32 v1, 16, v3
	v_fmac_f32_e32 v0, v1, v1
	v_and_b32_e32 v1, 0xffff0000, v3
	v_fmac_f32_e32 v0, v1, v1
	v_and_b32_e32 v7, 0xffff0000, v8
	v_lshlrev_b32_e32 v8, 16, v8
	v_fmac_f32_e32 v0, v8, v8
	v_lshlrev_b32_e32 v6, 16, v9
	v_fmac_f32_e32 v0, v7, v7
	s_waitcnt lgkmcnt(0)
	v_and_b32_e32 v5, 0xffff0000, v9
	v_fmac_f32_e32 v0, v6, v6
	v_lshlrev_b32_e32 v4, 16, v10
	v_fmac_f32_e32 v0, v5, v5
	v_and_b32_e32 v3, 0xffff0000, v10
	v_fmac_f32_e32 v0, v4, v4
	v_lshlrev_b32_e32 v2, 16, v11
	v_fmac_f32_e32 v0, v3, v3
	v_and_b32_e32 v1, 0xffff0000, v11
	v_fmac_f32_e32 v0, v2, v2
	v_fmac_f32_e32 v0, v1, v1
	s_nop 1
	v_mov_b32_dpp v1, v0 quad_perm:[1,0,3,2] row_mask:0xf bank_mask:0xf
	s_waitcnt lgkmcnt(0)
	v_add_f32_e32 v0, v0, v1
	s_nop 1
	v_mov_b32_dpp v1, v0 quad_perm:[2,3,0,1] row_mask:0xf bank_mask:0xf
	s_waitcnt lgkmcnt(0)
	v_add_f32_e32 v0, v0, v1
	s_nop 1
	v_mov_b32_dpp v1, v0 row_shl:4 row_mask:0xf bank_mask:0x5
	s_nop 1
	v_mov_b32_dpp v1, v0 row_shr:4 row_mask:0xf bank_mask:0xa
	s_and_saveexec_b64 s[4:5], s[0:1]
	s_cbranch_execz .LBB0_753
	s_waitcnt lgkmcnt(0)
	v_add_f32_e32 v0, v0, v1
	v_fmamk_f32 v0, v0, 0x3c000000, v184
	v_mul_f32_e32 v1, 0x4b800000, v0
	v_cmp_gt_f32_e64 s[0:1], s13, v0
	s_nop 1
	v_cndmask_b32_e64 v0, v0, v1, s[0:1]
	v_rsq_f32_e32 v0, v0
	s_nop 0
	v_mul_f32_e32 v1, 0x45800000, v0
	v_cndmask_b32_e64 v0, v0, v1, s[0:1]
	ds_write_b32 v27, v0 offset:768

.Lres_skip_355:
	v_and_b32_e32 v56, 0xffff0000, v23
	v_lshlrev_b32_e32 v58, 16, v23
	v_lshlrev_b32_e32 v94, 16, v19
	v_cndmask_b32_e32 v57, 0, v56, vcc
	v_cndmask_b32_e32 v56, 0, v58, vcc
	v_pk_add_f32 v[96:97], v[56:57], v[94:95] neg_lo:[0,1] neg_hi:[0,1]
	v_and_b32_e32 v56, 0xffff0000, v7
	v_lshlrev_b32_e32 v58, 16, v7
	v_and_b32_e32 v61, 0xffff0000, v3
	v_lshlrev_b32_e32 v60, 16, v3
	v_cndmask_b32_e32 v57, 0, v56, vcc
	v_cndmask_b32_e32 v56, 0, v58, vcc
	v_pk_add_f32 v[62:63], v[56:57], v[60:61] neg_lo:[0,1] neg_hi:[0,1]
	v_pk_fma_f32 v[88:89], v[62:63], v[50:51], v[60:61]
	v_and_b32_e32 v60, 0xffff0000, v15
	v_lshlrev_b32_e32 v62, 16, v15
	v_and_b32_e32 v51, 0xffff0000, v11
	v_lshlrev_b32_e32 v50, 16, v11
	v_cndmask_b32_e32 v61, 0, v60, vcc
	v_cndmask_b32_e32 v60, 0, v62, vcc
	v_pk_add_f32 v[60:61], v[60:61], v[50:51] neg_lo:[0,1] neg_hi:[0,1]
	v_lshlrev_b32_e32 v62, 16, v6
	v_pk_fma_f32 v[100:101], v[60:61], v[74:75], v[50:51]
	v_and_b32_e32 v60, 0xffff0000, v6
	v_and_b32_e32 v51, 0xffff0000, v2
	v_lshlrev_b32_e32 v50, 16, v2
	v_cndmask_b32_e32 v61, 0, v60, vcc
	v_cndmask_b32_e32 v60, 0, v62, vcc
	v_pk_add_f32 v[60:61], v[60:61], v[50:51] neg_lo:[0,1] neg_hi:[0,1]
	v_and_b32_e32 v75, 0xffff0000, v10
	v_pk_fma_f32 v[86:87], v[60:61], v[48:49], v[50:51]
	v_and_b32_e32 v48, 0xffff0000, v14
	v_lshlrev_b32_e32 v50, 16, v14
	v_lshlrev_b32_e32 v74, 16, v10
	v_cndmask_b32_e32 v49, 0, v48, vcc
	v_cndmask_b32_e32 v48, 0, v50, vcc
	v_pk_add_f32 v[78:79], v[48:49], v[74:75] neg_lo:[0,1] neg_hi:[0,1]
	v_pk_fma_f32 v[102:103], v[78:79], v[72:73], v[74:75]
	v_and_b32_e32 v74, 0xffff0000, v5
	v_lshlrev_b32_e32 v77, 16, v5
	v_and_b32_e32 v73, 0xffff0000, v1
	v_lshlrev_b32_e32 v72, 16, v1
	v_cndmask_b32_e32 v75, 0, v74, vcc
	v_cndmask_b32_e32 v74, 0, v77, vcc
	v_pk_add_f32 v[74:75], v[74:75], v[72:73] neg_lo:[0,1] neg_hi:[0,1]
	ds_read2_b32 v[80:81], v76 offset1:1
	v_pk_fma_f32 v[92:93], v[66:67], v[74:75], v[72:73]
	v_and_b32_e32 v72, 0xffff0000, v13
	v_lshlrev_b32_e32 v74, 16, v13
	v_and_b32_e32 v67, 0xffff0000, v9
	v_lshlrev_b32_e32 v66, 16, v9
	v_cndmask_b32_e32 v73, 0, v72, vcc
	v_cndmask_b32_e32 v72, 0, v74, vcc
	v_pk_add_f32 v[72:73], v[72:73], v[66:67] neg_lo:[0,1] neg_hi:[0,1]
	v_lshlrev_b32_e32 v74, 16, v12
	v_pk_fma_f32 v[104:105], v[72:73], v[70:71], v[66:67]
	v_and_b32_e32 v70, 0xffff0000, v4
	v_lshlrev_b32_e32 v72, 16, v4
	v_and_b32_e32 v67, 0xffff0000, v0
	v_lshlrev_b32_e32 v66, 16, v0
	v_cndmask_b32_e32 v71, 0, v70, vcc
	v_cndmask_b32_e32 v70, 0, v72, vcc
	v_pk_add_f32 v[70:71], v[70:71], v[66:67] neg_lo:[0,1] neg_hi:[0,1]
	v_and_b32_e32 v72, 0xffff0000, v12
	v_pk_fma_f32 v[90:91], v[64:65], v[70:71], v[66:67]
	v_and_b32_e32 v71, 0xffff0000, v8
	v_lshlrev_b32_e32 v70, 16, v8
	v_cndmask_b32_e32 v73, 0, v72, vcc
	v_cndmask_b32_e32 v72, 0, v74, vcc
	v_pk_add_f32 v[72:73], v[72:73], v[70:71] neg_lo:[0,1] neg_hi:[0,1]
	v_add_u32_e32 v99, 0x4100, v76
	v_pk_fma_f32 v[106:107], v[72:73], v[68:69], v[70:71]
	v_add_u32_e32 v83, 0x4108, v76
	v_add_u32_e32 v98, 0x4110, v76
	v_add_u32_e32 v82, 0x4118, v76
	ds_read2_b32 v[108:109], v76 offset0:2 offset1:3
	ds_read2_b32 v[110:111], v76 offset0:4 offset1:5
	ds_read2_b32 v[112:113], v76 offset0:6 offset1:7
	s_waitcnt vmcnt(0) lgkmcnt(3)
	v_mov_b32_e32 v52, v212
	v_mov_b32_e32 v53, v213
	v_mov_b32_e32 v54, v214
	v_add_f32_e32 v52, v52, v80
	v_mul_f32_e64 v68, |v52|, s91
	v_exp_f32_e32 v80, v68
	ds_read2_b32 v[150:151], v99 offset1:1
	ds_read2_b32 v[118:119], v83 offset1:1
	ds_read2_b32 v[116:117], v98 offset1:1
	ds_read2_b32 v[114:115], v82 offset1:1
	v_add_f32_e32 v80, 1.0, v80
	v_cmp_gt_f32_e32 vcc, s3, v80
	s_and_b32 s0, s0, 0xfffff000
	s_or_b32 s4, s4, s0
	v_cndmask_b32_e64 v99, 0, 32, vcc
	v_ldexp_f32 v80, v80, v99
	v_log_f32_e32 v80, v80
	v_max_f32_e64 v52, -v52, 0
	s_waitcnt vmcnt(0) lgkmcnt(3)
	v_mov_b32_e32 v56, v216
	v_mov_b32_e32 v57, v217
	v_add_f32_e32 v56, v56, v150
	v_mul_f32_e32 v56, 0xbfb8aa3b, v56
	v_mul_f32_e32 v82, 0x3f317217, v80
	v_fma_f32 v82, v80, s10, -v82
	v_fmac_f32_e32 v82, 0x3377d1cf, v80
	v_fmac_f32_e32 v82, 0x3f317217, v80
	v_cmp_lt_f32_e64 s[0:1], |v80|, s11
	v_add_f32_e32 v53, v53, v81
	v_exp_f32_e32 v56, v56
	v_cndmask_b32_e64 v80, v80, v82, s[0:1]
	v_cndmask_b32_e32 v82, 0, v128, vcc
	v_sub_f32_e32 v80, v80, v82
	v_add_f32_e32 v52, v52, v80
	v_mul_f32_e64 v80, |v53|, s91
	v_exp_f32_e32 v80, v80
	v_sub_f32_e32 v52, -0.5, v52
	v_mul_f32_e32 v52, 0x3fb8aa3b, v52
	v_exp_f32_e32 v98, v52
	v_add_f32_e32 v52, 1.0, v56
	v_rcp_f32_e32 v56, v52
	v_add_f32_e32 v52, 1.0, v80
	v_cmp_gt_f32_e32 vcc, s3, v52
	v_add_f32_e32 v57, v57, v151
	v_max_f32_e64 v53, -v53, 0
	v_cndmask_b32_e64 v80, 0, 32, vcc
	v_ldexp_f32 v52, v52, v80
	v_log_f32_e32 v52, v52
	s_waitcnt vmcnt(0)
	v_mov_b32_e32 v48, v220
	v_mov_b32_e32 v49, v221
	v_mov_b32_e32 v50, v222
	v_mov_b32_e32 v51, v223
	v_mul_f32_e32 v149, v106, v224
	v_add_f32_e32 v54, v54, v108
	v_mul_f32_e32 v150, v107, v225
	v_mul_f32_e32 v60, 0x3f317217, v52
	v_fma_f32 v60, v52, s10, -v60
	v_fmac_f32_e32 v60, 0x3377d1cf, v52
	v_fmac_f32_e32 v60, 0x3f317217, v52
	v_cmp_lt_f32_e64 s[0:1], |v52|, s11
	v_add_f32_e32 v48, v48, v110
	v_add_f32_e32 v49, v49, v111
	v_cndmask_b32_e64 v52, v52, v60, s[0:1]
	v_cndmask_b32_e32 v60, 0, v128, vcc
	v_sub_f32_e32 v52, v52, v60
	v_add_f32_e32 v52, v53, v52
	v_mul_f32_e32 v53, 0xbfb8aa3b, v57
	v_exp_f32_e32 v53, v53
	v_sub_f32_e32 v52, -0.5, v52
	v_mul_f32_e32 v52, 0x3fb8aa3b, v52
	v_exp_f32_e32 v99, v52
	v_add_f32_e32 v52, 1.0, v53
	v_rcp_f32_e32 v57, v52
	v_mul_f32_e64 v52, |v54|, s91
	v_exp_f32_e32 v60, v52
	v_readlane_b32 s74, v241, 51
	v_pk_add_f32 v[52:53], v[56:57], -1.0 op_sel_hi:[1,0]
	v_readlane_b32 s75, v241, 52
	v_add_f32_e32 v60, 1.0, v60
	v_cmp_gt_f32_e32 vcc, s3, v60
	s_waitcnt vmcnt(0)
	v_pk_fma_f32 v[52:53], v[228:229], v[52:53], 1.0 op_sel_hi:[1,1,0]
	v_add_f32_e32 v50, v50, v112
	v_cndmask_b32_e64 v61, 0, 32, vcc
	v_ldexp_f32 v60, v60, v61
	v_log_f32_e32 v64, v60
	v_pk_mul_f32 v[60:61], v[106:107], v[52:53]
	v_max_f32_e64 v53, -v54, 0
	s_waitcnt lgkmcnt(2)
	v_add_f32_e32 v52, v218, v118
	v_mul_f32_e32 v54, 0x3f317217, v64
	v_fma_f32 v54, v64, s10, -v54
	v_fmac_f32_e32 v54, 0x3377d1cf, v64
	v_fmac_f32_e32 v54, 0x3f317217, v64
	v_cmp_lt_f32_e64 s[0:1], |v64|, s11
	v_cndmask_b32_e32 v58, 0, v128, vcc
	v_mul_f32_e32 v52, 0xbfb8aa3b, v52
	v_cndmask_b32_e64 v54, v64, v54, s[0:1]
	v_sub_f32_e32 v54, v54, v58
	v_add_f32_e32 v53, v53, v54
	v_sub_f32_e32 v53, -0.5, v53
	v_mul_f32_e32 v53, 0x3fb8aa3b, v53
	v_exp_f32_e32 v58, v53
	v_add_f32_e32 v53, v215, v109
	v_exp_f32_e32 v52, v52
	v_mul_f32_e64 v54, |v53|, s91
	v_exp_f32_e32 v54, v54
	v_max_f32_e64 v53, -v53, 0
	v_add_f32_e32 v52, 1.0, v52
	v_rcp_f32_e32 v64, v52
	v_add_f32_e32 v52, 1.0, v54
	v_cmp_gt_f32_e32 vcc, s3, v52
	v_mul_f32_e32 v106, v104, v226
	v_mul_f32_e32 v107, v105, v227
	v_cndmask_b32_e64 v54, 0, 32, vcc
	v_ldexp_f32 v52, v52, v54
	v_log_f32_e32 v52, v52
	v_add_f32_e32 v54, v219, v119
	v_add_f32_e32 v51, v51, v113
	v_mul_f32_e32 v55, 0x3f317217, v52
	v_fma_f32 v55, v52, s10, -v55
	v_fmac_f32_e32 v55, 0x3377d1cf, v52
	v_fmac_f32_e32 v55, 0x3f317217, v52
	v_cmp_lt_f32_e64 s[0:1], |v52|, s11
	v_mul_f32_e32 v151, v150, v150
	v_fmac_f32_e32 v151, v149, v149
	v_cndmask_b32_e64 v52, v52, v55, s[0:1]
	v_cndmask_b32_e32 v55, 0, v128, vcc
	v_sub_f32_e32 v52, v52, v55
	v_add_f32_e32 v52, v53, v52
	v_mul_f32_e32 v53, 0xbfb8aa3b, v54
	v_exp_f32_e32 v53, v53
	v_sub_f32_e32 v52, -0.5, v52
	v_mul_f32_e32 v52, 0x3fb8aa3b, v52
	v_exp_f32_e32 v59, v52
	v_add_f32_e32 v52, 1.0, v53
	v_rcp_f32_e32 v65, v52
	v_mul_f32_e64 v52, |v48|, s91
	v_exp_f32_e32 v54, v52
	v_max_f32_e64 v48, -v48, 0
	v_pk_add_f32 v[52:53], v[64:65], -1.0 op_sel_hi:[1,0]
	v_fmac_f32_e32 v151, v106, v106
	v_add_f32_e32 v54, 1.0, v54
	v_cmp_gt_f32_e32 vcc, s3, v54
	v_pk_fma_f32 v[52:53], v[230:231], v[52:53], 1.0 op_sel_hi:[1,1,0]
	v_fmac_f32_e32 v151, v107, v107
	v_cndmask_b32_e64 v55, 0, 32, vcc
	v_ldexp_f32 v54, v54, v55
	v_log_f32_e32 v54, v54
	v_pk_mul_f32 v[62:63], v[104:105], v[52:53]
	s_waitcnt vmcnt(0) lgkmcnt(1)
	v_add_f32_e32 v52, v232, v116
	v_mul_f32_e32 v52, 0xbfb8aa3b, v52
	v_mul_f32_e32 v53, 0x3f317217, v54
	v_fma_f32 v53, v54, s10, -v53
	v_fmac_f32_e32 v53, 0x3377d1cf, v54
	v_fmac_f32_e32 v53, 0x3f317217, v54
	v_cmp_lt_f32_e64 s[0:1], |v54|, s11
	v_exp_f32_e32 v52, v52
	s_waitcnt vmcnt(0)
	v_mul_f32_e32 v76, v102, v236
	v_cndmask_b32_e64 v53, v54, v53, s[0:1]
	v_cndmask_b32_e32 v54, 0, v128, vcc
	v_sub_f32_e32 v53, v53, v54
	v_add_f32_e32 v48, v48, v53
	v_mul_f32_e64 v53, |v49|, s91
	v_exp_f32_e32 v53, v53
	v_add_f32_e32 v52, 1.0, v52
	v_rcp_f32_e32 v66, v52
	v_max_f32_e64 v49, -v49, 0
	v_add_f32_e32 v52, 1.0, v53
	v_cmp_gt_f32_e32 vcc, s3, v52
	v_mul_f32_e64 v72, |v50|, s91
	v_exp_f32_e32 v104, v72
	v_cndmask_b32_e64 v53, 0, 32, vcc
	v_ldexp_f32 v52, v52, v53
	v_log_f32_e32 v52, v52
	v_add_f32_e32 v53, v233, v117
	v_mul_f32_e32 v77, v103, v237
	v_max_f32_e64 v50, -v50, 0
	v_mul_f32_e32 v54, 0x3f317217, v52
	v_fma_f32 v54, v52, s10, -v54
	v_fmac_f32_e32 v54, 0x3377d1cf, v52
	v_fmac_f32_e32 v54, 0x3f317217, v52
	v_cmp_lt_f32_e64 s[0:1], |v52|, s11
	v_fmac_f32_e32 v151, v76, v76
	v_fmac_f32_e32 v151, v77, v77
	v_cndmask_b32_e64 v52, v52, v54, s[0:1]
	v_cndmask_b32_e32 v54, 0, v128, vcc
	v_sub_f32_e32 v52, v52, v54
	v_add_f32_e32 v49, v49, v52
	v_mul_f32_e32 v52, 0xbfb8aa3b, v53
	v_exp_f32_e32 v67, v52
	v_pk_fma_f32 v[46:47], v[96:97], v[46:47], v[94:95]
	v_sub_f32_e32 v48, -0.5, v48
	v_add_f32_e32 v67, 1.0, v67
	v_rcp_f32_e32 v67, v67
	v_sub_f32_e32 v49, -0.5, v49
	v_mul_f32_e32 v48, 0x3fb8aa3b, v48
	v_mul_f32_e32 v49, 0x3fb8aa3b, v49
	v_pk_add_f32 v[72:73], v[66:67], -1.0 op_sel_hi:[1,0]
	v_exp_f32_e32 v48, v48
	s_waitcnt vmcnt(0)
	v_mov_b32_e32 v68, v244
	v_mov_b32_e32 v69, v245
	v_mov_b32_e32 v70, v246
	v_mov_b32_e32 v71, v247
	v_pk_fma_f32 v[68:69], v[68:69], v[72:73], 1.0 op_sel_hi:[1,1,0]
	v_add_f32_e32 v72, 1.0, v104
	v_cmp_gt_f32_e32 vcc, s3, v72
	v_pk_mul_f32 v[68:69], v[102:103], v[68:69]
	v_exp_f32_e32 v49, v49
	v_cndmask_b32_e64 v73, 0, 32, vcc
	v_ldexp_f32 v72, v72, v73
	v_log_f32_e32 v72, v72
	s_waitcnt lgkmcnt(0)
	v_add_f32_e32 v73, v234, v114
	v_and_b32_e32 v140, 63, v137
	v_readlane_b32 s37, v241, 34
	v_mul_f32_e32 v78, 0x3f317217, v72
	v_fma_f32 v78, v72, s10, -v78
	v_fmac_f32_e32 v78, 0x3377d1cf, v72
	v_fmac_f32_e32 v78, 0x3f317217, v72
	v_cmp_lt_f32_e64 s[0:1], |v72|, s11
	v_readlane_b32 s38, v241, 35
	v_readlane_b32 s39, v241, 36
	v_cndmask_b32_e64 v72, v72, v78, s[0:1]
	v_cndmask_b32_e32 v78, 0, v128, vcc
	v_sub_f32_e32 v72, v72, v78
	v_add_f32_e32 v50, v50, v72
	v_mul_f32_e32 v72, 0xbfb8aa3b, v73
	v_mul_f32_e64 v73, |v51|, s91
	v_exp_f32_e32 v73, v73
	v_mul_f32_e32 v78, v100, v238
	v_exp_f32_e32 v72, v72
	v_max_f32_e64 v51, -v51, 0
	v_add_f32_e32 v73, 1.0, v73
	v_cmp_gt_f32_e32 vcc, s3, v73
	v_add_f32_e32 v72, 1.0, v72
	v_rcp_f32_e32 v72, v72
	v_cndmask_b32_e64 v74, 0, 32, vcc
	v_ldexp_f32 v73, v73, v74
	v_log_f32_e32 v73, v73
	v_add_f32_e32 v74, v235, v115
	v_mul_f32_e32 v74, 0xbfb8aa3b, v74
	v_exp_f32_e32 v74, v74
	v_mul_f32_e32 v79, 0x3f317217, v73
	v_fma_f32 v79, v73, s10, -v79
	v_fmac_f32_e32 v79, 0x3377d1cf, v73
	v_fmac_f32_e32 v79, 0x3f317217, v73
	v_cmp_lt_f32_e64 s[0:1], |v73|, s11
	v_fmac_f32_e32 v151, v78, v78
	v_sub_f32_e32 v50, -0.5, v50
	v_cndmask_b32_e64 v73, v73, v79, s[0:1]
	v_cndmask_b32_e32 v79, 0, v128, vcc
	v_sub_f32_e32 v73, v73, v79
	v_add_f32_e32 v51, v51, v73
	v_add_f32_e32 v73, 1.0, v74
	v_rcp_f32_e32 v73, v73
	v_mul_f32_e32 v79, v101, v239
	v_cmp_lt_i32_e32 vcc, v130, v131
	v_fmac_f32_e32 v151, v79, v79
	v_pk_add_f32 v[74:75], v[72:73], -1.0 op_sel_hi:[1,0]
	v_sub_f32_e32 v51, -0.5, v51
	v_pk_fma_f32 v[70:71], v[70:71], v[74:75], 1.0 op_sel_hi:[1,1,0]
	v_cndmask_b32_e32 v74, v129, v130, vcc
	v_pk_mul_f32 v[70:71], v[100:101], v[70:71]
	v_lshlrev_b32_e32 v100, 2, v74
	v_pk_mul_f32 v[74:75], v[90:91], v[60:61]
	v_cmp_lt_i32_e32 vcc, v132, v131
	s_waitcnt vmcnt(0)
	v_pk_mul_f32 v[74:75], v[74:75], v[248:249]
	v_mul_f32_e32 v50, 0x3fb8aa3b, v50
	v_add_f32_e32 v74, 0, v74
	v_add_f32_e32 v80, v74, v75
	v_pk_mul_f32 v[74:75], v[92:93], v[62:63]
	v_mul_f32_e32 v51, 0x3fb8aa3b, v51
	v_pk_mul_f32 v[74:75], v[74:75], v[250:251]
	v_mov_b32_e32 v81, v43
	v_add_f32_e32 v74, v80, v74
	v_add_f32_e32 v80, v74, v75
	v_pk_mul_f32 v[74:75], v[86:87], v[68:69]
	v_exp_f32_e32 v50, v50
	s_waitcnt vmcnt(0)
	v_mov_b32_e32 v52, v252
	v_mov_b32_e32 v53, v253
	v_pk_mul_f32 v[52:53], v[74:75], v[52:53]
	v_exp_f32_e32 v51, v51
	v_add_f32_e32 v52, v80, v52
	v_add_f32_e32 v74, v52, v53
	v_pk_mul_f32 v[52:53], v[88:89], v[70:71]
	v_lshlrev_b32_e32 v80, 1, v146
	v_pk_mul_f32 v[52:53], v[52:53], v[254:255]
	v_cndmask_b32_e32 v54, v129, v132, vcc
	v_add_f32_e32 v52, v74, v52
	v_add_f32_e32 v52, v52, v53
	s_nop 1
	v_mov_b32_dpp v53, v52 quad_perm:[1,0,3,2] row_mask:0xf bank_mask:0xf
	v_lshlrev_b32_e32 v54, 2, v54
	v_cmp_lt_i32_e32 vcc, v133, v131
	s_nop 1
	v_mov_b32_dpp v55, v151 quad_perm:[1,0,3,2] row_mask:0xf bank_mask:0xf
	s_movk_i32 s0, 0x820
	s_waitcnt lgkmcnt(1)
	v_add_f32_e32 v52, v52, v53
	s_nop 1
	v_mov_b32_dpp v53, v52 quad_perm:[2,3,0,1] row_mask:0xf bank_mask:0xf
	v_cndmask_b32_e32 v74, v129, v133, vcc
	v_lshlrev_b32_e32 v82, 2, v74
	s_waitcnt lgkmcnt(1)
	v_add_f32_e32 v83, v151, v55
	s_nop 1
	v_mov_b32_dpp v100, v83 quad_perm:[2,3,0,1] row_mask:0xf bank_mask:0xf
	s_waitcnt lgkmcnt(1)
	v_add_f32_e32 v52, v52, v53
	s_nop 1
	v_mov_b32_dpp v53, v52 row_shl:4 row_mask:0xf bank_mask:0x5
	s_nop 1
	v_mov_b32_dpp v53, v52 row_shr:4 row_mask:0xf bank_mask:0xa
	v_cmp_lt_i32_e32 vcc, 0, v138
	v_readlane_b32 s44, v241, 41
	v_readlane_b32 s45, v241, 42
	v_readlane_b32 s48, v241, 45
	s_waitcnt lgkmcnt(0)
	v_add_f32_e32 v74, v52, v53
	v_pk_mul_f32 v[52:53], v[40:41], v[74:75] op_sel_hi:[1,0]
	v_pk_mul_f32 v[54:55], v[84:85], v[74:75] op_sel_hi:[1,0]
	v_cvt_pk_bf16_f32 v52, v52, v53
	v_cvt_pk_bf16_f32 v53, v54, v55
	v_pk_mul_f32 v[54:55], v[44:45], v[74:75] op_sel_hi:[1,0]
	v_pk_mul_f32 v[74:75], v[46:47], v[74:75] op_sel_hi:[1,0]
	v_cvt_pk_bf16_f32 v54, v54, v55
	v_cvt_pk_bf16_f32 v55, v74, v75
	v_add_u32_e32 v74, s4, v141
	v_ashrrev_i32_e32 v75, 31, v74
	v_lshlrev_b64 v[74:75], 10, v[74:75]
	v_lshl_add_u64 v[74:75], s[52:53], 0, v[74:75]
	v_lshl_add_u64 v[74:75], v[74:75], 0, v[80:81]
	global_store_dwordx4 v[74:75], v[52:55], off nt
	s_waitcnt lgkmcnt(0)
	s_barrier
	v_readlane_b32 s49, v241, 46
	v_add3_u32 v54, s94, v148, v144
	v_pk_add_f32 v[52:53], v[98:99], 0 neg_lo:[1,1] neg_hi:[1,1]
	ds_write2_b32 v54, v52, v53 offset1:1
	v_pk_add_f32 v[52:53], v[58:59], 0 neg_lo:[1,1] neg_hi:[1,1]
	ds_write2_b32 v54, v52, v53 offset0:2 offset1:3
	v_pk_add_f32 v[52:53], v[48:49], 0 neg_lo:[1,1] neg_hi:[1,1]
	ds_write2_b32 v54, v52, v53 offset0:4 offset1:5
	v_pk_add_f32 v[52:53], v[50:51], 0 neg_lo:[1,1] neg_hi:[1,1]
	ds_write2_b32 v54, v52, v53 offset0:6 offset1:7
	v_lshl_add_u32 v52, v140, 2, s94
	v_mul_lo_u32 v53, v138, s0
	s_waitcnt lgkmcnt(0)
	s_barrier
	v_add_u32_e32 v53, v52, v53
	ds_read2_b32 v[74:75], v53 offset1:65
	v_add_f32_e32 v55, v83, v100
	ds_bpermute_b32 v80, v82, v55
	ds_read2_b32 v[82:83], v53 offset0:130 offset1:195
	v_readlane_b32 s76, v241, 53
	s_waitcnt lgkmcnt(2)
	v_add_f32_e32 v52, 0, v74
	v_add_f32_e32 v81, v52, v75
	ds_write2_b32 v53, v52, v81 offset1:65
	v_add_u32_e32 v52, 0x400, v53
	ds_read2_b32 v[74:75], v52 offset0:4 offset1:69
	s_waitcnt lgkmcnt(2)
	v_add_f32_e32 v81, v81, v82
	v_add_f32_e32 v94, v81, v83
	ds_read2_b32 v[82:83], v52 offset0:134 offset1:199
	ds_write2_b32 v53, v81, v94 offset0:130 offset1:195
	s_waitcnt lgkmcnt(2)
	v_add_f32_e32 v74, v94, v74
	v_add_f32_e32 v75, v74, v75
	ds_write2_b32 v52, v74, v75 offset0:4 offset1:69
	s_waitcnt lgkmcnt(2)
	v_add_f32_e32 v74, v75, v82
	v_add_f32_e32 v75, v74, v83
	ds_write2_b32 v52, v74, v75 offset0:134 offset1:199
	v_lshl_add_u32 v74, v137, 2, 0
	v_add_u32_e32 v74, 0x24000, v74
	ds_write_b32 v74, v75
	s_waitcnt lgkmcnt(0)
	s_barrier
	v_mov_b32_e32 v81, 0
	v_readlane_b32 s77, v241, 54
	v_readlane_b32 s78, v241, 55
	v_readlane_b32 s79, v241, 56
	v_readlane_b32 s80, v241, 57
	v_readlane_b32 s81, v241, 58
	v_readlane_b32 s82, v241, 59
	v_readlane_b32 s83, v241, 60
	v_readlane_b32 s84, v241, 61
	v_readlane_b32 s85, v241, 62
	v_readlane_b32 s86, v241, 63
	v_readlane_b32 s87, v240, 0
	s_and_saveexec_b64 s[0:1], vcc
	s_cbranch_execz .LBB0_783
	v_cmp_lt_u32_e32 vcc, 7, v138
	v_mov_b32_e32 v81, 0
	v_mov_b32_e32 v74, 0
	s_and_saveexec_b64 s[4:5], vcc
	s_cbranch_execz .LBB0_778
	s_add_i32 s6, 0, 0x24000
	v_and_b32_e32 v74, 0x7ffffff8, v138
	v_lshl_add_u32 v75, v140, 2, s6
	s_mov_b32 s12, 0
	v_mov_b32_e32 v81, 0
	s_mov_b64 s[6:7], 0

.Lp5_math:
	v_lshlrev_b32_e32 v68, 16, v74
	v_and_b32_e32 v69, 0xffff0000, v74
	v_lshlrev_b32_e32 v70, 16, v75
	v_and_b32_e32 v71, 0xffff0000, v75
	s_nop 0
	v_lshlrev_b32_e32 v72, 16, v76
	v_and_b32_e32 v73, 0xffff0000, v76
	v_lshlrev_b32_e32 v74, 16, v77
	v_and_b32_e32 v75, 0xffff0000, v77
	s_nop 0
	v_mfma_f32_16x16x32_bf16 v[28:31], v[28:31], v[60:63], v[68:71]
	s_nop 0
	v_lshlrev_b32_e32 v19, 16, v192
	v_and_b32_e32 v77, 0xffff0000, v193
	s_nop 0
	v_lshlrev_b32_e32 v76, 16, v201
	v_mfma_f32_16x16x32_bf16 v[36:39], v[36:39], v[60:63], v[72:75]
	v_lshlrev_b32_e32 v68, 16, v78
	v_and_b32_e32 v69, 0xffff0000, v78
	v_lshlrev_b32_e32 v70, 16, v79
	v_and_b32_e32 v71, 0xffff0000, v79
	v_lshlrev_b32_e32 v72, 16, v80
	v_and_b32_e32 v73, 0xffff0000, v80
	v_lshlrev_b32_e32 v74, 16, v81
	v_and_b32_e32 v75, 0xffff0000, v81
	v_mfma_f32_16x16x32_bf16 v[44:47], v[44:47], v[60:63], v[68:71]
	v_and_b32_e32 v78, 0xffff0000, v201
	v_mfma_f32_16x16x32_bf16 v[52:55], v[52:55], v[60:63], v[72:75]
	s_nop 2
	v_and_b32_e32 v73, 0xffff0000, v192
	v_lshlrev_b32_e32 v75, 16, v193
	v_mfma_f32_16x16x32_bf16 v[28:31], v[32:35], v[64:67], v[28:31]
	v_lshlrev_b32_e32 v72, 16, v200
	v_and_b32_e32 v74, 0xffff0000, v200
	s_nop 0
	v_mfma_f32_16x16x32_bf16 v[32:35], v[40:43], v[64:67], v[36:39]
	v_mfma_f32_16x16x32_bf16 v[36:39], v[48:51], v[64:67], v[44:47]
	s_nop 2
	v_mov_b32_e32 v48, v30
	s_nop 2
	v_mov_b32_e32 v49, v34
	v_mov_b32_e32 v50, v31
	v_mfma_f32_16x16x32_bf16 v[40:43], v[56:59], v[64:67], v[52:55]
	v_mov_b32_e32 v44, v28
	v_mov_b32_e32 v45, v32
	v_mov_b32_e32 v46, v29
	v_mov_b32_e32 v47, v33
	v_pk_add_f32 v[44:45], v[44:45], v[46:47]
	v_mov_b32_e32 v51, v35
	v_mov_b32_e32 v46, v36
	s_nop 0
	v_mov_b32_e32 v47, v40
	v_mov_b32_e32 v52, v37
	v_mov_b32_e32 v53, v41
	v_pk_add_f32 v[44:45], v[48:49], v[44:45]
	v_mov_b32_e32 v54, v38
	v_mov_b32_e32 v55, v42
	v_pk_add_f32 v[46:47], v[46:47], v[52:53]
	v_pk_add_f32 v[44:45], v[50:51], v[44:45]
	v_mov_b32_e32 v56, v39
	v_mov_b32_e32 v57, v43
	v_pk_add_f32 v[46:47], v[54:55], v[46:47]
	v_add_f32_e32 v2, 0, v44
	v_pk_add_f32 v[46:47], v[56:57], v[46:47]
	v_add_f32_e32 v2, v2, v45
	v_add_f32_e32 v2, v2, v46
	v_add_f32_e32 v2, v2, v47
	v_mov_b32_e32 v44, v2
	s_nop 1
	v_permlane16_swap_b32_e32 v44, v2
	s_waitcnt lgkmcnt(0)
	v_add_f32_e32 v2, v2, v44
	v_mov_b32_e32 v44, v2
	s_nop 1
	v_permlane32_swap_b32_e32 v44, v2
	s_waitcnt lgkmcnt(0)
	v_add_f32_e32 v44, v2, v44
	v_fmamk_f32 v49, v44, 0xbc800000, v29
	v_fmamk_f32 v48, v44, 0xbc800000, v28
	v_mul_f32_e32 v52, v49, v49
	v_fmamk_f32 v30, v44, 0xbc800000, v30
	v_fmac_f32_e32 v52, v48, v48
	v_fmac_f32_e32 v31, 0xbc800000, v44
	v_fmac_f32_e32 v52, v30, v30
	v_fmamk_f32 v50, v44, 0xbc800000, v32
	v_fmac_f32_e32 v52, v31, v31
	v_fmamk_f32 v51, v44, 0xbc800000, v33
	v_fmac_f32_e32 v52, v50, v50
	v_mul_f32_e32 v2, 0x3c800000, v44
	v_fmamk_f32 v34, v44, 0xbc800000, v34
	v_fmac_f32_e32 v52, v51, v51
	v_fmac_f32_e32 v35, 0xbc800000, v44
	v_pk_add_f32 v[28:29], v[36:37], v[2:3] op_sel_hi:[1,0] neg_lo:[0,1] neg_hi:[0,1]
	v_fmac_f32_e32 v52, v34, v34
	v_pk_add_f32 v[36:37], v[40:41], v[2:3] op_sel_hi:[1,0] neg_lo:[0,1] neg_hi:[0,1]
	v_pk_mul_f32 v[40:41], v[28:29], v[28:29]
	v_fmac_f32_e32 v52, v35, v35
	v_pk_add_f32 v[32:33], v[38:39], v[2:3] op_sel_hi:[1,0] neg_lo:[0,1] neg_hi:[0,1]
	v_pk_add_f32 v[38:39], v[42:43], v[2:3] op_sel_hi:[1,0] neg_lo:[0,1] neg_hi:[0,1]
	v_add_f32_e32 v2, v40, v52
	v_pk_mul_f32 v[42:43], v[32:33], v[32:33]
	v_add_f32_e32 v2, v41, v2
	v_add_f32_e32 v2, v42, v2
	v_pk_mul_f32 v[44:45], v[36:37], v[36:37]
	v_add_f32_e32 v2, v43, v2
	v_add_f32_e32 v2, v44, v2
	v_pk_mul_f32 v[46:47], v[38:39], v[38:39]
	v_add_f32_e32 v2, v45, v2
	v_add_f32_e32 v2, v46, v2
	v_add_f32_e32 v2, v47, v2
	v_mov_b32_e32 v40, v2
	s_nop 1
	v_permlane16_swap_b32_e32 v40, v2
	s_nop 0
	v_and_b32_e32 v43, 0xffff0000, v195
	v_lshlrev_b32_e32 v42, 16, v203
	v_and_b32_e32 v44, 0xffff0000, v203
	s_waitcnt lgkmcnt(0)
	v_add_f32_e32 v2, v2, v40
	v_mov_b32_e32 v40, v2
	s_nop 1
	v_permlane32_swap_b32_e32 v40, v2
	s_waitcnt lgkmcnt(0)
	v_add_f32_e32 v2, v2, v40
	v_fmamk_f32 v2, v2, 0x3c800000, v18
	v_mul_f32_e32 v40, 0x4b800000, v2
	v_cmp_gt_f32_e32 vcc, s9, v2
	s_nop 1
	v_cndmask_b32_e32 v2, v2, v40, vcc
	v_rsq_f32_e32 v2, v2
	s_nop 0
	v_mul_f32_e32 v40, 0x45800000, v2
	v_cndmask_b32_e32 v2, v2, v40, vcc
	v_mul_f32_e32 v40, v48, v2
	v_mul_f32_e32 v41, v49, v2
	v_mul_f32_e32 v30, v30, v2
	v_mul_f32_e32 v31, v31, v2
	s_waitcnt vmcnt(22)
	v_fma_f32 v20, v20, v40, v24
	v_fma_f32 v21, v21, v41, v25
	v_fma_f32 v22, v22, v30, v26
	v_fmac_f32_e32 v27, v23, v31
	v_add_f32_e32 v19, v20, v19
	v_add_f32_e32 v20, v21, v73
	v_add_f32_e32 v21, v22, v75
	v_add_f32_e32 v22, v27, v77
	v_mul_f32_e32 v19, v19, v72
	v_mul_f32_e32 v20, v20, v74
	v_mul_f32_e32 v21, v21, v76
	v_mul_f32_e32 v22, v22, v78
	v_cvt_pk_bf16_f32 v20, v19, v20
	v_cvt_pk_bf16_f32 v21, v21, v22
	global_store_dwordx2 v[14:15], v[20:21], off offset:1024
	v_mul_f32_e32 v45, v50, v2
	v_mul_f32_e32 v46, v51, v2
	v_mul_f32_e32 v34, v34, v2
	v_mul_f32_e32 v35, v35, v2
	v_lshlrev_b32_e32 v19, 16, v194
	v_and_b32_e32 v31, 0xffff0000, v194
	v_lshlrev_b32_e32 v41, 16, v195
	v_lshlrev_b32_e32 v30, 16, v202
	v_and_b32_e32 v40, 0xffff0000, v202
	v_mul_f32_e32 v28, v28, v2
	v_mul_f32_e32 v29, v29, v2
	v_mul_f32_e32 v32, v32, v2
	v_mul_f32_e32 v33, v33, v2
	v_cmp_lt_i32_e32 vcc, s10, v1
	s_or_b64 s[4:5], vcc, s[4:5]
	v_fma_f32 v20, v96, v45, v100
	v_fma_f32 v21, v97, v46, v101
	v_fma_f32 v22, v98, v34, v102
	v_fma_f32 v27, v99, v35, v103
	v_add_f32_e32 v19, v20, v19
	v_add_f32_e32 v20, v21, v31
	v_add_f32_e32 v21, v22, v41
	v_add_f32_e32 v22, v27, v43
	v_mul_f32_e32 v19, v19, v30
	v_mul_f32_e32 v20, v20, v40
	v_mul_f32_e32 v21, v21, v42
	v_mul_f32_e32 v22, v22, v44
	v_cvt_pk_bf16_f32 v20, v19, v20
	v_cvt_pk_bf16_f32 v21, v21, v22
	global_store_dwordx2 v[14:15], v[20:21], off offset:1056
	v_lshlrev_b32_e32 v19, 16, v196
	v_and_b32_e32 v31, 0xffff0000, v196
	v_lshlrev_b32_e32 v35, 16, v197
	v_and_b32_e32 v41, 0xffff0000, v197
	v_lshlrev_b32_e32 v30, 16, v204
	v_and_b32_e32 v34, 0xffff0000, v204
	v_lshlrev_b32_e32 v40, 16, v205
	v_and_b32_e32 v42, 0xffff0000, v205
	v_fma_f32 v20, v104, v28, v108
	v_fma_f32 v21, v105, v29, v109
	v_fma_f32 v22, v106, v32, v110
	v_fma_f32 v27, v107, v33, v111
	v_add_f32_e32 v19, v20, v19
	v_add_f32_e32 v20, v21, v31
	v_add_f32_e32 v21, v22, v35
	v_add_f32_e32 v22, v27, v41
	v_mul_f32_e32 v19, v19, v30
	v_mul_f32_e32 v20, v20, v34
	v_mul_f32_e32 v21, v21, v40
	v_mul_f32_e32 v22, v22, v42
	v_cvt_pk_bf16_f32 v20, v19, v20
	v_cvt_pk_bf16_f32 v21, v21, v22
	global_store_dwordx2 v[14:15], v[20:21], off offset:1088
	v_mul_f32_e32 v35, v36, v2
	v_mul_f32_e32 v36, v37, v2
	v_mul_f32_e32 v37, v38, v2
	v_mul_f32_e32 v2, v39, v2
	v_lshlrev_b32_e32 v19, 16, v198
	v_and_b32_e32 v29, 0xffff0000, v198
	v_lshlrev_b32_e32 v31, 16, v199
	v_and_b32_e32 v33, 0xffff0000, v199
	v_lshlrev_b32_e32 v28, 16, v206
	v_and_b32_e32 v30, 0xffff0000, v206
	v_lshlrev_b32_e32 v32, 16, v207
	v_and_b32_e32 v34, 0xffff0000, v207
	v_fma_f32 v20, v112, v35, v116
	v_fma_f32 v21, v36, v113, v117
	v_fma_f32 v22, v37, v114, v118
	v_fma_f32 v27, v2, v115, v119
	v_add_f32_e32 v2, v20, v19
	v_add_f32_e32 v19, v21, v29
	v_add_f32_e32 v20, v22, v31
	v_add_f32_e32 v21, v27, v33
	v_mul_f32_e32 v2, v2, v28
	v_mul_f32_e32 v19, v19, v30
	v_mul_f32_e32 v22, v20, v32
	v_mul_f32_e32 v21, v21, v34
	v_cvt_pk_bf16_f32 v20, v2, v19
	v_cvt_pk_bf16_f32 v21, v22, v21
	global_store_dwordx2 v[14:15], v[20:21], off offset:1120
	s_andn2_b64 exec, exec, s[4:5]
	s_cbranch_execnz .LBB0_1118
